# MFMA blocks in snake order (one A/B operand change per instruction) in the fp8 and bf16 K-loops
# baseline (speedup 1.0000x reference)
; #define G_STAGE(bufoff, gbase, voff) do { _Pragma("unroll") for (int _i = 0; _i < 2; ++_i) \
;         __builtin_amdgcn_global_load_lds((const unsigned*)((const char*)(gbase) + (voff)[_i]), (LAS unsigned*)(lds + (bufoff) + ldsw + _i * 8192), 16, 0, 0); } while (0)
; #define G_WAIT_V(n) asm volatile("s_waitcnt vmcnt(" #n ")" ::: "memory")
; #define G_WAIT_L(n) asm volatile("s_waitcnt lgkmcnt(" #n ")" ::: "memory")
; #define G_BAR __builtin_amdgcn_s_barrier()
; #define G_SCHED __builtin_amdgcn_sched_barrier(0)
; template <int MODE  , class Epi, class Sched>
; __device__ __forceinline__ void gemm_phase(LAS unsigned char* lds, const GemmDesc g, const Sched& S, const Epi& E) {
;     ...
;             G_LDB(B0, 0, 0); G_SCHED; G_LDA(At, 0, 0); G_STAGE(G_SA(1, 1), a1 + hstepA, voffA);
;             G_WAIT_L(8); G_BAR; G_WAIT_L(0); G_MMA(0, 0, At, B0); G_BAR; G_SCHED;
;             G_LDB(B1, 0, 1); G_STAGE(G_SB(0, 0), b2, voffB);
;             G_BAR; G_WAIT_L(0); G_MMA(0, 1, At, B1); G_BAR;
;             G_LDA(At, 0, 1); G_STAGE(G_SA(0, 0), a2, voffA);
;             G_BAR; G_WAIT_L(0); G_MMA(1, 0, At, B0); G_BAR; G_SCHED;
;             G_STAGE(G_SB(0, 1), b2 + hstepB, voffB);
;             G_WAIT_V(6); G_BAR; G_MMA(1, 1, At, B1); G_BAR;
.Lnodb_p1b:
.LBB0_737:
	ds_read_b128 v[2:5], v168
	ds_read_b128 v[6:9], v168 offset:1024
	ds_read_b128 v[10:13], v168 offset:2048
	ds_read_b128 v[14:17], v168 offset:3072
	s_add_u32 s46, s50, 0x100
	s_addc_u32 s47, s51, 0
	s_cmp_eq_u32 s79, 12
	s_cselect_b32 s55, s45, s47
	s_cselect_b32 s54, s44, s46
	s_cselect_b32 s53, s3, s78
	s_cselect_b32 s52, s2, s77
	s_add_u32 s98, s50, 0x44080
	s_addc_u32 s99, s51, 0
	s_add_i32 m0, s62, 0xc000
	ds_read_b128 v[174:177], v169
	ds_read_b128 v[178:181], v169 offset:1024
	ds_read_b128 v[182:185], v169 offset:2048
	ds_read_b128 v[186:189], v169 offset:3072
	ds_read_b128 v[192:195], v169 offset:4096
	ds_read_b128 v[196:199], v169 offset:5120
	ds_read_b128 v[200:203], v169 offset:6144
	ds_read_b128 v[204:207], v169 offset:7168
	global_load_lds_dwordx4 v152, s[98:99]
	s_add_i32 m0, s62, 0xe000
	s_nop 0
	global_load_lds_dwordx4 v148, s[98:99]
	s_waitcnt lgkmcnt(8)
	s_barrier
	s_waitcnt lgkmcnt(0)
	v_mfma_scale_f32_16x16x128_f8f6f4 v[142:145], v[2:9], v[174:181], v[142:145], v170, v170 op_sel_hi:[0,0,0]
	v_mfma_scale_f32_16x16x128_f8f6f4 v[138:141], v[10:17], v[174:181], v[138:141], v170, v170 op_sel_hi:[0,0,0]
	v_mfma_scale_f32_16x16x128_f8f6f4 v[122:125], v[10:17], v[182:189], v[122:125], v170, v170 op_sel_hi:[0,0,0]
	v_mfma_scale_f32_16x16x128_f8f6f4 v[126:129], v[2:9], v[182:189], v[126:129], v170, v170 op_sel_hi:[0,0,0]
	v_mfma_scale_f32_16x16x128_f8f6f4 v[110:113], v[2:9], v[192:199], v[110:113], v170, v170 op_sel_hi:[0,0,0]
	v_mfma_scale_f32_16x16x128_f8f6f4 v[106:109], v[10:17], v[192:199], v[106:109], v170, v170 op_sel_hi:[0,0,0]
	v_mfma_scale_f32_16x16x128_f8f6f4 v[90:93], v[10:17], v[200:207], v[90:93], v170, v170 op_sel_hi:[0,0,0]
	v_mfma_scale_f32_16x16x128_f8f6f4 v[94:97], v[2:9], v[200:207], v[94:97], v170, v170 op_sel_hi:[0,0,0]
	s_barrier
	s_add_i32 s0, s69, s60
	s_mov_b32 m0, s0
	ds_read_b128 v[208:211], v171
	ds_read_b128 v[212:215], v171 offset:1024
	ds_read_b128 v[216:219], v171 offset:2048
	ds_read_b128 v[220:223], v171 offset:3072
	global_load_lds_dwordx4 v150, s[52:53]
	s_add_i32 m0, s0, 0x2000
	s_nop 0
	global_load_lds_dwordx4 v146, s[52:53]
	s_barrier
	s_waitcnt lgkmcnt(0)
	v_mfma_scale_f32_16x16x128_f8f6f4 v[134:137], v[208:215], v[174:181], v[134:137], v170, v170 op_sel_hi:[0,0,0]
	v_mfma_scale_f32_16x16x128_f8f6f4 v[130:133], v[216:223], v[174:181], v[130:133], v170, v170 op_sel_hi:[0,0,0]
	v_mfma_scale_f32_16x16x128_f8f6f4 v[114:117], v[216:223], v[182:189], v[114:117], v170, v170 op_sel_hi:[0,0,0]
	v_mfma_scale_f32_16x16x128_f8f6f4 v[118:121], v[208:215], v[182:189], v[118:121], v170, v170 op_sel_hi:[0,0,0]
	v_mfma_scale_f32_16x16x128_f8f6f4 v[102:105], v[208:215], v[192:199], v[102:105], v170, v170 op_sel_hi:[0,0,0]
	v_mfma_scale_f32_16x16x128_f8f6f4 v[98:101], v[216:223], v[192:199], v[98:101], v170, v170 op_sel_hi:[0,0,0]
	v_mfma_scale_f32_16x16x128_f8f6f4 v[82:85], v[216:223], v[200:207], v[82:85], v170, v170 op_sel_hi:[0,0,0]
	v_mfma_scale_f32_16x16x128_f8f6f4 v[86:89], v[208:215], v[200:207], v[86:89], v170, v170 op_sel_hi:[0,0,0]
	s_mov_b32 m0, s62
	s_barrier
	ds_read_b128 v[174:177], v169 offset:16384
	ds_read_b128 v[178:181], v169 offset:17408
	ds_read_b128 v[182:185], v169 offset:18432
	ds_read_b128 v[186:189], v169 offset:19456
	ds_read_b128 v[192:195], v169 offset:20480
	ds_read_b128 v[196:199], v169 offset:21504
	ds_read_b128 v[200:203], v169 offset:22528
	ds_read_b128 v[204:207], v169 offset:23552
	global_load_lds_dwordx4 v152, s[54:55]
	s_mov_b32 m0, s63
	s_nop 0
	global_load_lds_dwordx4 v148, s[54:55]
	s_barrier
	s_waitcnt lgkmcnt(0)
	v_mfma_scale_f32_16x16x128_f8f6f4 v[78:81], v[2:9], v[174:181], v[78:81], v170, v170 op_sel_hi:[0,0,0]
	v_mfma_scale_f32_16x16x128_f8f6f4 v[74:77], v[10:17], v[174:181], v[74:77], v170, v170 op_sel_hi:[0,0,0]
	v_mfma_scale_f32_16x16x128_f8f6f4 v[58:61], v[10:17], v[182:189], v[58:61], v170, v170 op_sel_hi:[0,0,0]
	v_mfma_scale_f32_16x16x128_f8f6f4 v[62:65], v[2:9], v[182:189], v[62:65], v170, v170 op_sel_hi:[0,0,0]
	v_mfma_scale_f32_16x16x128_f8f6f4 v[46:49], v[2:9], v[192:199], v[46:49], v170, v170 op_sel_hi:[0,0,0]
	v_mfma_scale_f32_16x16x128_f8f6f4 v[42:45], v[10:17], v[192:199], v[42:45], v170, v170 op_sel_hi:[0,0,0]
	v_mfma_scale_f32_16x16x128_f8f6f4 v[26:29], v[10:17], v[200:207], v[26:29], v170, v170 op_sel_hi:[0,0,0]
	v_mfma_scale_f32_16x16x128_f8f6f4 v[30:33], v[2:9], v[200:207], v[30:33], v170, v170 op_sel_hi:[0,0,0]
	s_barrier
	s_add_u32 s0, s52, 0x44000
	s_addc_u32 s1, s53, 0
	s_add_i32 s10, s70, s60
	s_mov_b32 m0, s10
	s_nop 0
	global_load_lds_dwordx4 v150, s[0:1]
	s_add_i32 m0, s10, 0x2000
	s_nop 0
	global_load_lds_dwordx4 v146, s[0:1]
	s_waitcnt vmcnt(6)
	s_barrier
	v_mfma_scale_f32_16x16x128_f8f6f4 v[70:73], v[208:215], v[174:181], v[70:73], v170, v170 op_sel_hi:[0,0,0]
	v_mfma_scale_f32_16x16x128_f8f6f4 v[66:69], v[216:223], v[174:181], v[66:69], v170, v170 op_sel_hi:[0,0,0]
	v_mfma_scale_f32_16x16x128_f8f6f4 v[50:53], v[216:223], v[182:189], v[50:53], v170, v170 op_sel_hi:[0,0,0]
	v_mfma_scale_f32_16x16x128_f8f6f4 v[54:57], v[208:215], v[182:189], v[54:57], v170, v170 op_sel_hi:[0,0,0]
	v_mfma_scale_f32_16x16x128_f8f6f4 v[38:41], v[208:215], v[192:199], v[38:41], v170, v170 op_sel_hi:[0,0,0]
	v_mfma_scale_f32_16x16x128_f8f6f4 v[34:37], v[216:223], v[192:199], v[34:37], v170, v170 op_sel_hi:[0,0,0]
	v_mfma_scale_f32_16x16x128_f8f6f4 v[18:21], v[216:223], v[200:207], v[18:21], v170, v170 op_sel_hi:[0,0,0]
	v_mfma_scale_f32_16x16x128_f8f6f4 v[22:25], v[208:215], v[200:207], v[22:25], v170, v170 op_sel_hi:[0,0,0]
	s_add_i32 s10, 0, 0x18000
	v_add_u32_e32 v14, s10, v166
	s_barrier
; #define G_STAGE(bufoff, gbase, voff) do { _Pragma("unroll") for (int _i = 0; _i < 2; ++_i) \
;         __builtin_amdgcn_global_load_lds((const unsigned*)((const char*)(gbase) + (voff)[_i]), (LAS unsigned*)(lds + (bufoff) + ldsw + _i * 8192), 16, 0, 0); } while (0)
; #define G_WAIT_V(n) asm volatile("s_waitcnt vmcnt(" #n ")" ::: "memory")
; #define G_WAIT_L(n) asm volatile("s_waitcnt lgkmcnt(" #n ")" ::: "memory")
; #define G_BAR __builtin_amdgcn_s_barrier()
; #define G_SCHED __builtin_amdgcn_sched_barrier(0)
; template <int MODE  , class Epi, class Sched>
; __device__ __forceinline__ void gemm_phase(LAS unsigned char* lds, const GemmDesc g, const Sched& S, const Epi& E) {
;     ...
;             G_LDB(B0, 1, 0); G_SCHED; G_LDA(At, 1, 0); G_STAGE(G_SA(0, 1), a2 + hstepA, voffA);
;             G_WAIT_L(8); G_BAR; G_WAIT_L(0); G_MMA(0, 0, At, B0); G_BAR; G_SCHED;
;             G_LDB(B1, 1, 1); G_STAGE(G_SB(1, 0), b3, voffB);
;             G_BAR; G_WAIT_L(0); G_MMA(0, 1, At, B1); G_BAR;
;             G_LDA(At, 1, 1); G_STAGE(G_SA(1, 0), a3, voffA);
;             G_BAR; G_WAIT_L(0); G_MMA(1, 0, At, B0); G_BAR; G_SCHED;
;             G_STAGE(G_SB(1, 1), b3 + hstepB, voffB);
;             G_WAIT_V(6); G_BAR; G_MMA(1, 1, At, B1); G_BAR;
	ds_read_b128 v[2:5], v14
	ds_read_b128 v[6:9], v14 offset:1024
	ds_read_b128 v[10:13], v14 offset:2048
	ds_read_b128 v[14:17], v14 offset:3072
	s_add_u32 s0, s54, 0x44000
	s_addc_u32 s1, s55, 0
	s_mov_b32 m0, s64
	ds_read_b128 v[174:177], v169 offset:32768
	ds_read_b128 v[178:181], v169 offset:33792
	ds_read_b128 v[182:185], v169 offset:34816
	ds_read_b128 v[186:189], v169 offset:35840
	ds_read_b128 v[192:195], v169 offset:36864
	ds_read_b128 v[196:199], v169 offset:37888
	ds_read_b128 v[200:203], v169 offset:38912
	ds_read_b128 v[204:207], v169 offset:39936
	global_load_lds_dwordx4 v152, s[0:1]
	s_mov_b32 m0, s65
	s_nop 0
	global_load_lds_dwordx4 v148, s[0:1]
	s_waitcnt lgkmcnt(8)
	s_barrier
	s_waitcnt lgkmcnt(0)
	v_mfma_scale_f32_16x16x128_f8f6f4 v[142:145], v[2:9], v[174:181], v[142:145], v170, v170 op_sel_hi:[0,0,0]
	v_mfma_scale_f32_16x16x128_f8f6f4 v[138:141], v[10:17], v[174:181], v[138:141], v170, v170 op_sel_hi:[0,0,0]
	v_mfma_scale_f32_16x16x128_f8f6f4 v[122:125], v[10:17], v[182:189], v[122:125], v170, v170 op_sel_hi:[0,0,0]
	v_mfma_scale_f32_16x16x128_f8f6f4 v[126:129], v[2:9], v[182:189], v[126:129], v170, v170 op_sel_hi:[0,0,0]
	v_mfma_scale_f32_16x16x128_f8f6f4 v[110:113], v[2:9], v[192:199], v[110:113], v170, v170 op_sel_hi:[0,0,0]
	v_mfma_scale_f32_16x16x128_f8f6f4 v[106:109], v[10:17], v[192:199], v[106:109], v170, v170 op_sel_hi:[0,0,0]
	v_mfma_scale_f32_16x16x128_f8f6f4 v[90:93], v[10:17], v[200:207], v[90:93], v170, v170 op_sel_hi:[0,0,0]
	v_mfma_scale_f32_16x16x128_f8f6f4 v[94:97], v[2:9], v[200:207], v[94:97], v170, v170 op_sel_hi:[0,0,0]
	s_barrier
	s_add_i32 s11, 0, 0x1c000
	s_add_i32 s0, s10, s60
	v_add_u32_e32 v173, s11, v166
	s_add_u32 s98, s52, 0x80
	s_addc_u32 s99, s53, 0
	s_mov_b32 m0, s0
	ds_read_b128 v[208:211], v173
	ds_read_b128 v[212:215], v173 offset:1024
	ds_read_b128 v[216:219], v173 offset:2048
	ds_read_b128 v[220:223], v173 offset:3072
	global_load_lds_dwordx4 v150, s[98:99]
	s_add_i32 m0, s0, 0x2000
	s_nop 0
	global_load_lds_dwordx4 v146, s[98:99]
	s_barrier
	s_waitcnt lgkmcnt(0)
	v_mfma_scale_f32_16x16x128_f8f6f4 v[134:137], v[208:215], v[174:181], v[134:137], v170, v170 op_sel_hi:[0,0,0]
	v_mfma_scale_f32_16x16x128_f8f6f4 v[130:133], v[216:223], v[174:181], v[130:133], v170, v170 op_sel_hi:[0,0,0]
	v_mfma_scale_f32_16x16x128_f8f6f4 v[114:117], v[216:223], v[182:189], v[114:117], v170, v170 op_sel_hi:[0,0,0]
	v_mfma_scale_f32_16x16x128_f8f6f4 v[118:121], v[208:215], v[182:189], v[118:121], v170, v170 op_sel_hi:[0,0,0]
	v_mfma_scale_f32_16x16x128_f8f6f4 v[102:105], v[208:215], v[192:199], v[102:105], v170, v170 op_sel_hi:[0,0,0]
	v_mfma_scale_f32_16x16x128_f8f6f4 v[98:101], v[216:223], v[192:199], v[98:101], v170, v170 op_sel_hi:[0,0,0]
	v_mfma_scale_f32_16x16x128_f8f6f4 v[82:85], v[216:223], v[200:207], v[82:85], v170, v170 op_sel_hi:[0,0,0]
	v_mfma_scale_f32_16x16x128_f8f6f4 v[86:89], v[208:215], v[200:207], v[86:89], v170, v170 op_sel_hi:[0,0,0]
	s_mov_b32 m0, s67
	s_add_u32 s98, s54, 0x80
	s_addc_u32 s99, s55, 0
	s_barrier
	ds_read_b128 v[174:177], v169 offset:49152
	ds_read_b128 v[178:181], v169 offset:50176
	ds_read_b128 v[182:185], v169 offset:51200
	ds_read_b128 v[186:189], v169 offset:52224
	ds_read_b128 v[192:195], v169 offset:53248
	ds_read_b128 v[196:199], v169 offset:54272
	ds_read_b128 v[200:203], v169 offset:55296
	ds_read_b128 v[204:207], v169 offset:56320
	global_load_lds_dwordx4 v152, s[98:99]
	s_mov_b32 m0, s68
	s_nop 0
	global_load_lds_dwordx4 v148, s[98:99]
	s_barrier
	s_waitcnt lgkmcnt(0)
	v_mfma_scale_f32_16x16x128_f8f6f4 v[78:81], v[2:9], v[174:181], v[78:81], v170, v170 op_sel_hi:[0,0,0]
	v_mfma_scale_f32_16x16x128_f8f6f4 v[74:77], v[10:17], v[174:181], v[74:77], v170, v170 op_sel_hi:[0,0,0]
	v_mfma_scale_f32_16x16x128_f8f6f4 v[58:61], v[10:17], v[182:189], v[58:61], v170, v170 op_sel_hi:[0,0,0]
	v_mfma_scale_f32_16x16x128_f8f6f4 v[62:65], v[2:9], v[182:189], v[62:65], v170, v170 op_sel_hi:[0,0,0]
	v_mfma_scale_f32_16x16x128_f8f6f4 v[46:49], v[2:9], v[192:199], v[46:49], v170, v170 op_sel_hi:[0,0,0]
	v_mfma_scale_f32_16x16x128_f8f6f4 v[42:45], v[10:17], v[192:199], v[42:45], v170, v170 op_sel_hi:[0,0,0]
	v_mfma_scale_f32_16x16x128_f8f6f4 v[26:29], v[10:17], v[200:207], v[26:29], v170, v170 op_sel_hi:[0,0,0]
	v_mfma_scale_f32_16x16x128_f8f6f4 v[30:33], v[2:9], v[200:207], v[30:33], v170, v170 op_sel_hi:[0,0,0]
	s_barrier
	s_add_u32 s0, s52, 0x44080
	s_addc_u32 s1, s53, 0
	s_add_i32 s10, s11, s60
	s_mov_b32 m0, s10
	s_nop 0
	global_load_lds_dwordx4 v150, s[0:1]
	s_add_i32 m0, s10, 0x2000
	s_nop 0
	global_load_lds_dwordx4 v146, s[0:1]
	s_waitcnt vmcnt(6)
	s_barrier
	v_mfma_scale_f32_16x16x128_f8f6f4 v[70:73], v[208:215], v[174:181], v[70:73], v170, v170 op_sel_hi:[0,0,0]
	s_add_i32 s79, s79, 2
	s_add_u32 s77, s77, 0x100
	s_addc_u32 s78, s78, 0
	s_cmp_gt_u32 s79, 13
	s_mov_b64 s[50:51], s[46:47]
	v_mfma_scale_f32_16x16x128_f8f6f4 v[66:69], v[216:223], v[174:181], v[66:69], v170, v170 op_sel_hi:[0,0,0]
	v_mfma_scale_f32_16x16x128_f8f6f4 v[50:53], v[216:223], v[182:189], v[50:53], v170, v170 op_sel_hi:[0,0,0]
	v_mfma_scale_f32_16x16x128_f8f6f4 v[54:57], v[208:215], v[182:189], v[54:57], v170, v170 op_sel_hi:[0,0,0]
	v_mfma_scale_f32_16x16x128_f8f6f4 v[38:41], v[208:215], v[192:199], v[38:41], v170, v170 op_sel_hi:[0,0,0]
	v_mfma_scale_f32_16x16x128_f8f6f4 v[34:37], v[216:223], v[192:199], v[34:37], v170, v170 op_sel_hi:[0,0,0]
	v_mfma_scale_f32_16x16x128_f8f6f4 v[18:21], v[216:223], v[200:207], v[18:21], v170, v170 op_sel_hi:[0,0,0]
	v_mfma_scale_f32_16x16x128_f8f6f4 v[22:25], v[208:215], v[200:207], v[22:25], v170, v170 op_sel_hi:[0,0,0]
	s_cbranch_scc1 .Lkdone_p1b
	s_barrier
	s_branch .LBB0_737

; #define G_STAGE(bufoff, gbase, voff) do { _Pragma("unroll") for (int _i = 0; _i < 2; ++_i) \
;         __builtin_amdgcn_global_load_lds((const unsigned*)((const char*)(gbase) + (voff)[_i]), (LAS unsigned*)(lds + (bufoff) + ldsw + _i * 8192), 16, 0, 0); } while (0)
; #define G_WAIT_V(n) asm volatile("s_waitcnt vmcnt(" #n ")" ::: "memory")
; #define G_WAIT_L(n) asm volatile("s_waitcnt lgkmcnt(" #n ")" ::: "memory")
; #define G_BAR __builtin_amdgcn_s_barrier()
; #define G_SCHED __builtin_amdgcn_sched_barrier(0)
; template <int MODE  , class Epi, class Sched>
; __device__ __forceinline__ void gemm_phase(LAS unsigned char* lds, const GemmDesc g, const Sched& S, const Epi& E) {
;     ...
;             G_LDB(B0, 0, 0); G_SCHED; G_LDA(At, 0, 0); G_STAGE(G_SA(1, 1), a1 + hstepA, voffA);
;             G_WAIT_L(8); G_BAR; G_WAIT_L(0); G_MMA(0, 0, At, B0); G_BAR; G_SCHED;
;             G_LDB(B1, 0, 1); G_STAGE(G_SB(0, 0), b2, voffB);
;             G_BAR; G_WAIT_L(0); G_MMA(0, 1, At, B1); G_BAR;
;             G_LDA(At, 0, 1); G_STAGE(G_SA(0, 0), a2, voffA);
;             G_BAR; G_WAIT_L(0); G_MMA(1, 0, At, B0); G_BAR; G_SCHED;
;             G_STAGE(G_SB(0, 1), b2 + hstepB, voffB);
;             G_WAIT_V(6); G_BAR; G_MMA(1, 1, At, B1); G_BAR;
.Lnodb_sa:
.LBB0_815:
	v_add_u32_e32 v142, s58, v172
	ds_read_b128 v[130:133], v142
	ds_read_b128 v[134:137], v142 offset:1024
	ds_read_b128 v[138:141], v142 offset:2048
	ds_read_b128 v[142:145], v142 offset:3072
	s_add_u32 s44, s42, 0x100
	s_addc_u32 s45, s43, 0
	s_cmp_eq_u32 s68, 12
	s_cselect_b32 s49, s35, s45
	s_cselect_b32 s48, s34, s44
	s_cselect_b32 s47, s3, s67
	s_cselect_b32 s46, s2, s21
	s_add_u32 s98, s42, 0x84080
	s_addc_u32 s99, s43, 0
	s_add_i32 m0, s52, 0xc000
	ds_read_b128 v[158:161], v174
	ds_read_b128 v[162:165], v174 offset:1024
	ds_read_b128 v[166:169], v174 offset:2048
	ds_read_b128 v[176:179], v174 offset:3072
	ds_read_b128 v[180:183], v174 offset:4096
	ds_read_b128 v[184:187], v174 offset:5120
	ds_read_b128 v[192:195], v174 offset:6144
	ds_read_b128 v[196:199], v174 offset:7168
	global_load_lds_dwordx4 v146, s[98:99]
	s_add_i32 m0, s52, 0xe000
	s_nop 0
	global_load_lds_dwordx4 v150, s[98:99]
	s_waitcnt lgkmcnt(8)
	s_barrier
	s_waitcnt lgkmcnt(0)
	v_mfma_f32_16x16x32_bf16 v[126:129], v[130:133], v[158:161], v[126:129]
	v_mfma_f32_16x16x32_bf16 v[122:125], v[138:141], v[158:161], v[122:125]
	v_mfma_f32_16x16x32_bf16 v[114:117], v[138:141], v[166:169], v[114:117]
	v_mfma_f32_16x16x32_bf16 v[118:121], v[130:133], v[166:169], v[118:121]
	v_mfma_f32_16x16x32_bf16 v[110:113], v[130:133], v[180:183], v[110:113]
	v_mfma_f32_16x16x32_bf16 v[106:109], v[138:141], v[180:183], v[106:109]
	v_mfma_f32_16x16x32_bf16 v[98:101], v[138:141], v[192:195], v[98:101]
	v_mfma_f32_16x16x32_bf16 v[102:105], v[130:133], v[192:195], v[102:105]
	v_mfma_f32_16x16x32_bf16 v[126:129], v[134:137], v[162:165], v[126:129]
	v_mfma_f32_16x16x32_bf16 v[122:125], v[142:145], v[162:165], v[122:125]
	v_mfma_f32_16x16x32_bf16 v[114:117], v[142:145], v[176:179], v[114:117]
	v_mfma_f32_16x16x32_bf16 v[118:121], v[134:137], v[176:179], v[118:121]
	v_mfma_f32_16x16x32_bf16 v[110:113], v[134:137], v[184:187], v[110:113]
	v_mfma_f32_16x16x32_bf16 v[106:109], v[142:145], v[184:187], v[106:109]
	v_mfma_f32_16x16x32_bf16 v[98:101], v[142:145], v[196:199], v[98:101]
	v_mfma_f32_16x16x32_bf16 v[102:105], v[134:137], v[196:199], v[102:105]
	s_barrier
	v_add_u32_e32 v170, s59, v172
	s_add_i32 s0, s58, s51
	ds_read_b128 v[200:203], v170
	ds_read_b128 v[204:207], v170 offset:1024
	ds_read_b128 v[208:211], v170 offset:2048
	ds_read_b128 v[212:215], v170 offset:3072
	s_mov_b32 m0, s0
	s_nop 0
	global_load_lds_dwordx4 v148, s[46:47]
	s_add_i32 m0, s0, 0x2000
	s_nop 0
	global_load_lds_dwordx4 v152, s[46:47]
	s_barrier
	s_waitcnt lgkmcnt(0)
	v_mfma_f32_16x16x32_bf16 v[94:97], v[200:203], v[158:161], v[94:97]
	v_mfma_f32_16x16x32_bf16 v[90:93], v[208:211], v[158:161], v[90:93]
	v_mfma_f32_16x16x32_bf16 v[82:85], v[208:211], v[166:169], v[82:85]
	v_mfma_f32_16x16x32_bf16 v[86:89], v[200:203], v[166:169], v[86:89]
	v_mfma_f32_16x16x32_bf16 v[78:81], v[200:203], v[180:183], v[78:81]
	v_mfma_f32_16x16x32_bf16 v[74:77], v[208:211], v[180:183], v[74:77]
	v_mfma_f32_16x16x32_bf16 v[66:69], v[208:211], v[192:195], v[66:69]
	v_mfma_f32_16x16x32_bf16 v[70:73], v[200:203], v[192:195], v[70:73]
	v_mfma_f32_16x16x32_bf16 v[94:97], v[204:207], v[162:165], v[94:97]
	v_mfma_f32_16x16x32_bf16 v[90:93], v[212:215], v[162:165], v[90:93]
	v_mfma_f32_16x16x32_bf16 v[82:85], v[212:215], v[176:179], v[82:85]
	v_mfma_f32_16x16x32_bf16 v[86:89], v[204:207], v[176:179], v[86:89]
	v_mfma_f32_16x16x32_bf16 v[78:81], v[204:207], v[184:187], v[78:81]
	v_mfma_f32_16x16x32_bf16 v[74:77], v[212:215], v[184:187], v[74:77]
	v_mfma_f32_16x16x32_bf16 v[66:69], v[212:215], v[196:199], v[66:69]
	v_mfma_f32_16x16x32_bf16 v[70:73], v[204:207], v[196:199], v[70:73]
	s_mov_b32 m0, s52
	s_barrier
	ds_read_b128 v[158:161], v174 offset:16384
	ds_read_b128 v[162:165], v174 offset:17408
	ds_read_b128 v[166:169], v174 offset:18432
	ds_read_b128 v[176:179], v174 offset:19456
	ds_read_b128 v[180:183], v174 offset:20480
	ds_read_b128 v[184:187], v174 offset:21504
	ds_read_b128 v[192:195], v174 offset:22528
	ds_read_b128 v[196:199], v174 offset:23552
	global_load_lds_dwordx4 v146, s[48:49]
	s_mov_b32 m0, s53
	s_nop 0
	global_load_lds_dwordx4 v150, s[48:49]
	s_barrier
	s_waitcnt lgkmcnt(0)
	v_mfma_f32_16x16x32_bf16 v[62:65], v[130:133], v[158:161], v[62:65]
	v_mfma_f32_16x16x32_bf16 v[58:61], v[138:141], v[158:161], v[58:61]
	v_mfma_f32_16x16x32_bf16 v[50:53], v[138:141], v[166:169], v[50:53]
	v_mfma_f32_16x16x32_bf16 v[54:57], v[130:133], v[166:169], v[54:57]
	v_mfma_f32_16x16x32_bf16 v[46:49], v[130:133], v[180:183], v[46:49]
	v_mfma_f32_16x16x32_bf16 v[42:45], v[138:141], v[180:183], v[42:45]
	v_mfma_f32_16x16x32_bf16 v[34:37], v[138:141], v[192:195], v[34:37]
	v_mfma_f32_16x16x32_bf16 v[38:41], v[130:133], v[192:195], v[38:41]
	v_mfma_f32_16x16x32_bf16 v[62:65], v[134:137], v[162:165], v[62:65]
	v_mfma_f32_16x16x32_bf16 v[58:61], v[142:145], v[162:165], v[58:61]
	v_mfma_f32_16x16x32_bf16 v[50:53], v[142:145], v[176:179], v[50:53]
	v_mfma_f32_16x16x32_bf16 v[54:57], v[134:137], v[176:179], v[54:57]
	v_mfma_f32_16x16x32_bf16 v[46:49], v[134:137], v[184:187], v[46:49]
	v_mfma_f32_16x16x32_bf16 v[42:45], v[142:145], v[184:187], v[42:45]
	v_mfma_f32_16x16x32_bf16 v[34:37], v[142:145], v[196:199], v[34:37]
	v_mfma_f32_16x16x32_bf16 v[38:41], v[134:137], v[196:199], v[38:41]
	s_barrier
	s_add_u32 s0, s46, 0x84000
	s_addc_u32 s1, s47, 0
	s_add_i32 s10, s59, s51
	s_mov_b32 m0, s10
	s_nop 0
	global_load_lds_dwordx4 v148, s[0:1]
	s_add_i32 m0, s10, 0x2000
	s_nop 0
	global_load_lds_dwordx4 v152, s[0:1]
	s_waitcnt vmcnt(6)
	s_barrier
; #define G_STAGE(bufoff, gbase, voff) do { _Pragma("unroll") for (int _i = 0; _i < 2; ++_i) \
;         __builtin_amdgcn_global_load_lds((const unsigned*)((const char*)(gbase) + (voff)[_i]), (LAS unsigned*)(lds + (bufoff) + ldsw + _i * 8192), 16, 0, 0); } while (0)
; #define G_WAIT_V(n) asm volatile("s_waitcnt vmcnt(" #n ")" ::: "memory")
; #define G_WAIT_L(n) asm volatile("s_waitcnt lgkmcnt(" #n ")" ::: "memory")
; #define G_BAR __builtin_amdgcn_s_barrier()
; #define G_SCHED __builtin_amdgcn_sched_barrier(0)
; template <int MODE  , class Epi, class Sched>
; __device__ __forceinline__ void gemm_phase(LAS unsigned char* lds, const GemmDesc g, const Sched& S, const Epi& E) {
;     ...
;             G_WAIT_V(6); G_BAR; G_MMA(1, 1, At, B1); G_BAR;
;             G_LDB(B0, 1, 0); G_SCHED; G_LDA(At, 1, 0); G_STAGE(G_SA(0, 1), a2 + hstepA, voffA);
;             G_WAIT_L(8); G_BAR; G_WAIT_L(0); G_MMA(0, 0, At, B0); G_BAR; G_SCHED;
;             G_LDB(B1, 1, 1); G_STAGE(G_SB(1, 0), b3, voffB);
;             G_BAR; G_WAIT_L(0); G_MMA(0, 1, At, B1); G_BAR;
	v_mfma_f32_16x16x32_bf16 v[30:33], v[200:203], v[158:161], v[30:33]
	v_mfma_f32_16x16x32_bf16 v[26:29], v[208:211], v[158:161], v[26:29]
	v_mfma_f32_16x16x32_bf16 v[18:21], v[208:211], v[166:169], v[18:21]
	v_mfma_f32_16x16x32_bf16 v[22:25], v[200:203], v[166:169], v[22:25]
	v_mfma_f32_16x16x32_bf16 v[14:17], v[200:203], v[180:183], v[14:17]
	v_mfma_f32_16x16x32_bf16 v[10:13], v[208:211], v[180:183], v[10:13]
	v_mfma_f32_16x16x32_bf16 v[2:5], v[208:211], v[192:195], v[2:5]
	v_mfma_f32_16x16x32_bf16 v[6:9], v[200:203], v[192:195], v[6:9]
	v_mfma_f32_16x16x32_bf16 v[30:33], v[204:207], v[162:165], v[30:33]
	v_mfma_f32_16x16x32_bf16 v[26:29], v[212:215], v[162:165], v[26:29]
	v_mfma_f32_16x16x32_bf16 v[18:21], v[212:215], v[176:179], v[18:21]
	v_mfma_f32_16x16x32_bf16 v[22:25], v[204:207], v[176:179], v[22:25]
	v_mfma_f32_16x16x32_bf16 v[14:17], v[204:207], v[184:187], v[14:17]
	v_mfma_f32_16x16x32_bf16 v[10:13], v[212:215], v[184:187], v[10:13]
	v_mfma_f32_16x16x32_bf16 v[2:5], v[212:215], v[196:199], v[2:5]
	v_mfma_f32_16x16x32_bf16 v[6:9], v[204:207], v[196:199], v[6:9]
	s_add_i32 s10, 0, 0x18000
	v_add_u32_e32 v142, s10, v172
	s_barrier
	ds_read_b128 v[130:133], v142
	ds_read_b128 v[134:137], v142 offset:1024
	ds_read_b128 v[138:141], v142 offset:2048
	ds_read_b128 v[142:145], v142 offset:3072
	s_add_u32 s0, s48, 0x84000
	s_addc_u32 s1, s49, 0
	s_mov_b32 m0, s54
	ds_read_b128 v[158:161], v174 offset:32768
	ds_read_b128 v[162:165], v174 offset:33792
	ds_read_b128 v[166:169], v174 offset:34816
	ds_read_b128 v[176:179], v174 offset:35840
	ds_read_b128 v[180:183], v174 offset:36864
	ds_read_b128 v[184:187], v174 offset:37888
	ds_read_b128 v[192:195], v174 offset:38912
	ds_read_b128 v[196:199], v174 offset:39936
	global_load_lds_dwordx4 v146, s[0:1]
	s_mov_b32 m0, s55
	s_nop 0
	global_load_lds_dwordx4 v150, s[0:1]
	s_waitcnt lgkmcnt(8)
	s_barrier
	s_waitcnt lgkmcnt(0)
	v_mfma_f32_16x16x32_bf16 v[126:129], v[130:133], v[158:161], v[126:129]
	v_mfma_f32_16x16x32_bf16 v[122:125], v[138:141], v[158:161], v[122:125]
	v_mfma_f32_16x16x32_bf16 v[114:117], v[138:141], v[166:169], v[114:117]
	v_mfma_f32_16x16x32_bf16 v[118:121], v[130:133], v[166:169], v[118:121]
	v_mfma_f32_16x16x32_bf16 v[110:113], v[130:133], v[180:183], v[110:113]
	v_mfma_f32_16x16x32_bf16 v[106:109], v[138:141], v[180:183], v[106:109]
	v_mfma_f32_16x16x32_bf16 v[98:101], v[138:141], v[192:195], v[98:101]
	v_mfma_f32_16x16x32_bf16 v[102:105], v[130:133], v[192:195], v[102:105]
	v_mfma_f32_16x16x32_bf16 v[126:129], v[134:137], v[162:165], v[126:129]
	v_mfma_f32_16x16x32_bf16 v[122:125], v[142:145], v[162:165], v[122:125]
	v_mfma_f32_16x16x32_bf16 v[114:117], v[142:145], v[176:179], v[114:117]
	v_mfma_f32_16x16x32_bf16 v[118:121], v[134:137], v[176:179], v[118:121]
	v_mfma_f32_16x16x32_bf16 v[110:113], v[134:137], v[184:187], v[110:113]
	v_mfma_f32_16x16x32_bf16 v[106:109], v[142:145], v[184:187], v[106:109]
	v_mfma_f32_16x16x32_bf16 v[98:101], v[142:145], v[196:199], v[98:101]
	v_mfma_f32_16x16x32_bf16 v[102:105], v[134:137], v[196:199], v[102:105]
	s_barrier
	s_add_i32 s11, 0, 0x1c000
	s_add_i32 s0, s10, s51
	v_add_u32_e32 v175, s11, v172
	s_add_u32 s98, s46, 0x80
	s_addc_u32 s99, s47, 0
	s_mov_b32 m0, s0
	ds_read_b128 v[200:203], v175
	ds_read_b128 v[204:207], v175 offset:1024
	ds_read_b128 v[208:211], v175 offset:2048
	ds_read_b128 v[212:215], v175 offset:3072
	global_load_lds_dwordx4 v148, s[98:99]
	s_add_i32 m0, s0, 0x2000
	s_nop 0
	global_load_lds_dwordx4 v152, s[98:99]
	s_barrier
; #define G_STAGE(bufoff, gbase, voff) do { _Pragma("unroll") for (int _i = 0; _i < 2; ++_i) \
;         __builtin_amdgcn_global_load_lds((const unsigned*)((const char*)(gbase) + (voff)[_i]), (LAS unsigned*)(lds + (bufoff) + ldsw + _i * 8192), 16, 0, 0); } while (0)
; #define G_WAIT_V(n) asm volatile("s_waitcnt vmcnt(" #n ")" ::: "memory")
; #define G_WAIT_L(n) asm volatile("s_waitcnt lgkmcnt(" #n ")" ::: "memory")
; #define G_BAR __builtin_amdgcn_s_barrier()
; #define G_SCHED __builtin_amdgcn_sched_barrier(0)
; template <int MODE  , class Epi, class Sched>
; __device__ __forceinline__ void gemm_phase(LAS unsigned char* lds, const GemmDesc g, const Sched& S, const Epi& E) {
;     ...
;             G_BAR; G_WAIT_L(0); G_MMA(0, 1, At, B1); G_BAR;
;             G_LDA(At, 1, 1); G_STAGE(G_SA(1, 0), a3, voffA);
;             G_BAR; G_WAIT_L(0); G_MMA(1, 0, At, B0); G_BAR; G_SCHED;
;             G_STAGE(G_SB(1, 1), b3 + hstepB, voffB);
;             G_WAIT_V(6); G_BAR; G_MMA(1, 1, At, B1); G_BAR;
	s_waitcnt lgkmcnt(0)
	v_mfma_f32_16x16x32_bf16 v[94:97], v[200:203], v[158:161], v[94:97]
	v_mfma_f32_16x16x32_bf16 v[90:93], v[208:211], v[158:161], v[90:93]
	v_mfma_f32_16x16x32_bf16 v[82:85], v[208:211], v[166:169], v[82:85]
	v_mfma_f32_16x16x32_bf16 v[86:89], v[200:203], v[166:169], v[86:89]
	v_mfma_f32_16x16x32_bf16 v[78:81], v[200:203], v[180:183], v[78:81]
	v_mfma_f32_16x16x32_bf16 v[74:77], v[208:211], v[180:183], v[74:77]
	v_mfma_f32_16x16x32_bf16 v[66:69], v[208:211], v[192:195], v[66:69]
	v_mfma_f32_16x16x32_bf16 v[70:73], v[200:203], v[192:195], v[70:73]
	v_mfma_f32_16x16x32_bf16 v[94:97], v[204:207], v[162:165], v[94:97]
	v_mfma_f32_16x16x32_bf16 v[90:93], v[212:215], v[162:165], v[90:93]
	v_mfma_f32_16x16x32_bf16 v[82:85], v[212:215], v[176:179], v[82:85]
	v_mfma_f32_16x16x32_bf16 v[86:89], v[204:207], v[176:179], v[86:89]
	v_mfma_f32_16x16x32_bf16 v[78:81], v[204:207], v[184:187], v[78:81]
	v_mfma_f32_16x16x32_bf16 v[74:77], v[212:215], v[184:187], v[74:77]
	v_mfma_f32_16x16x32_bf16 v[66:69], v[212:215], v[196:199], v[66:69]
	v_mfma_f32_16x16x32_bf16 v[70:73], v[204:207], v[196:199], v[70:73]
	s_mov_b32 m0, s56
	s_add_u32 s98, s48, 0x80
	s_addc_u32 s99, s49, 0
	s_barrier
	ds_read_b128 v[158:161], v174 offset:49152
	ds_read_b128 v[162:165], v174 offset:50176
	ds_read_b128 v[166:169], v174 offset:51200
	ds_read_b128 v[176:179], v174 offset:52224
	ds_read_b128 v[180:183], v174 offset:53248
	ds_read_b128 v[184:187], v174 offset:54272
	ds_read_b128 v[192:195], v174 offset:55296
	ds_read_b128 v[196:199], v174 offset:56320
	global_load_lds_dwordx4 v146, s[98:99]
	s_mov_b32 m0, s57
	s_nop 0
	global_load_lds_dwordx4 v150, s[98:99]
	s_barrier
	s_waitcnt lgkmcnt(0)
	v_mfma_f32_16x16x32_bf16 v[62:65], v[130:133], v[158:161], v[62:65]
	v_mfma_f32_16x16x32_bf16 v[58:61], v[138:141], v[158:161], v[58:61]
	v_mfma_f32_16x16x32_bf16 v[50:53], v[138:141], v[166:169], v[50:53]
	v_mfma_f32_16x16x32_bf16 v[54:57], v[130:133], v[166:169], v[54:57]
	v_mfma_f32_16x16x32_bf16 v[46:49], v[130:133], v[180:183], v[46:49]
	v_mfma_f32_16x16x32_bf16 v[42:45], v[138:141], v[180:183], v[42:45]
	v_mfma_f32_16x16x32_bf16 v[34:37], v[138:141], v[192:195], v[34:37]
	v_mfma_f32_16x16x32_bf16 v[38:41], v[130:133], v[192:195], v[38:41]
	v_mfma_f32_16x16x32_bf16 v[62:65], v[134:137], v[162:165], v[62:65]
	v_mfma_f32_16x16x32_bf16 v[58:61], v[142:145], v[162:165], v[58:61]
	v_mfma_f32_16x16x32_bf16 v[50:53], v[142:145], v[176:179], v[50:53]
	v_mfma_f32_16x16x32_bf16 v[54:57], v[134:137], v[176:179], v[54:57]
	v_mfma_f32_16x16x32_bf16 v[46:49], v[134:137], v[184:187], v[46:49]
	v_mfma_f32_16x16x32_bf16 v[42:45], v[142:145], v[184:187], v[42:45]
	v_mfma_f32_16x16x32_bf16 v[34:37], v[142:145], v[196:199], v[34:37]
	v_mfma_f32_16x16x32_bf16 v[38:41], v[134:137], v[196:199], v[38:41]
	s_barrier
	s_add_u32 s0, s46, 0x84080
	s_addc_u32 s1, s47, 0
	s_add_i32 s10, s11, s51
	s_mov_b32 m0, s10
	s_nop 0
	global_load_lds_dwordx4 v148, s[0:1]
	s_add_i32 m0, s10, 0x2000
	s_nop 0
	global_load_lds_dwordx4 v152, s[0:1]
	s_waitcnt vmcnt(6)
	s_barrier
	v_mfma_f32_16x16x32_bf16 v[30:33], v[200:203], v[158:161], v[30:33]
	s_add_i32 s68, s68, 2
	s_add_u32 s21, s21, 0x100
	s_addc_u32 s67, s67, 0
	s_cmp_gt_u32 s68, 13
	s_mov_b64 s[42:43], s[44:45]
	v_mfma_f32_16x16x32_bf16 v[26:29], v[208:211], v[158:161], v[26:29]
	v_mfma_f32_16x16x32_bf16 v[18:21], v[208:211], v[166:169], v[18:21]
	v_mfma_f32_16x16x32_bf16 v[22:25], v[200:203], v[166:169], v[22:25]
	v_mfma_f32_16x16x32_bf16 v[14:17], v[200:203], v[180:183], v[14:17]
	v_mfma_f32_16x16x32_bf16 v[10:13], v[208:211], v[180:183], v[10:13]
	v_mfma_f32_16x16x32_bf16 v[2:5], v[208:211], v[192:195], v[2:5]
	v_mfma_f32_16x16x32_bf16 v[6:9], v[200:203], v[192:195], v[6:9]
	v_mfma_f32_16x16x32_bf16 v[30:33], v[204:207], v[162:165], v[30:33]
	v_mfma_f32_16x16x32_bf16 v[26:29], v[212:215], v[162:165], v[26:29]
	v_mfma_f32_16x16x32_bf16 v[18:21], v[212:215], v[176:179], v[18:21]
	v_mfma_f32_16x16x32_bf16 v[22:25], v[204:207], v[176:179], v[22:25]
	v_mfma_f32_16x16x32_bf16 v[14:17], v[204:207], v[184:187], v[14:17]
	v_mfma_f32_16x16x32_bf16 v[10:13], v[212:215], v[184:187], v[10:13]
	v_mfma_f32_16x16x32_bf16 v[2:5], v[212:215], v[196:199], v[2:5]
	v_mfma_f32_16x16x32_bf16 v[6:9], v[204:207], v[196:199], v[6:9]
	s_cbranch_scc1 .Lkdone_sa
	s_barrier
	s_branch .LBB0_815

; #define G_STAGE(bufoff, gbase, voff) do { _Pragma("unroll") for (int _i = 0; _i < 2; ++_i) \
;         __builtin_amdgcn_global_load_lds((const unsigned*)((const char*)(gbase) + (voff)[_i]), (LAS unsigned*)(lds + (bufoff) + ldsw + _i * 8192), 16, 0, 0); } while (0)
; #define G_WAIT_V(n) asm volatile("s_waitcnt vmcnt(" #n ")" ::: "memory")
; #define G_WAIT_L(n) asm volatile("s_waitcnt lgkmcnt(" #n ")" ::: "memory")
; #define G_BAR __builtin_amdgcn_s_barrier()
; #define G_SCHED __builtin_amdgcn_sched_barrier(0)
; template <int MODE  , class Epi, class Sched>
; __device__ __forceinline__ void gemm_phase(LAS unsigned char* lds, const GemmDesc g, const Sched& S, const Epi& E) {
;     ...
;             G_LDB(B0, 0, 0); G_SCHED; G_LDA(At, 0, 0); G_STAGE(G_SA(1, 1), a1 + hstepA, voffA);
;             G_WAIT_L(8); G_BAR; G_WAIT_L(0); G_MMA(0, 0, At, B0); G_BAR; G_SCHED;
;             G_LDB(B1, 0, 1); G_STAGE(G_SB(0, 0), b2, voffB);
;             G_BAR; G_WAIT_L(0); G_MMA(0, 1, At, B1); G_BAR;
;             G_LDA(At, 0, 1); G_STAGE(G_SA(0, 0), a2, voffA);
;             G_BAR; G_WAIT_L(0); G_MMA(1, 0, At, B0); G_BAR; G_SCHED;
;             G_STAGE(G_SB(0, 1), b2 + hstepB, voffB);
;             G_WAIT_V(6); G_BAR; G_MMA(1, 1, At, B1); G_BAR;
.Lnodb_sb:
.LBB0_897:
	v_add_u32_e32 v142, s57, v174
	ds_read_b128 v[130:133], v142
	ds_read_b128 v[134:137], v142 offset:1024
	ds_read_b128 v[138:141], v142 offset:2048
	ds_read_b128 v[142:145], v142 offset:3072
	s_add_u32 s42, s40, 0x100
	s_addc_u32 s43, s41, 0
	s_cmp_eq_u32 s71, 12
	s_cselect_b32 s47, s21, s43
	s_cselect_b32 s46, s20, s42
	s_cselect_b32 s45, s3, s70
	s_cselect_b32 s44, s2, s19
	s_add_u32 s98, s40, 0x84080
	s_addc_u32 s99, s41, 0
	s_add_i32 m0, s50, 0xc000
	ds_read_b128 v[158:161], v176
	ds_read_b128 v[162:165], v176 offset:1024
	ds_read_b128 v[166:169], v176 offset:2048
	ds_read_b128 v[170:173], v176 offset:3072
	ds_read_b128 v[178:181], v176 offset:4096
	ds_read_b128 v[182:185], v176 offset:5120
	ds_read_b128 v[186:189], v176 offset:6144
	ds_read_b128 v[192:195], v176 offset:7168
	global_load_lds_dwordx4 v146, s[98:99]
	s_add_i32 m0, s50, 0xe000
	s_nop 0
	global_load_lds_dwordx4 v150, s[98:99]
	s_waitcnt lgkmcnt(8)
	s_barrier
	s_waitcnt lgkmcnt(0)
	v_mfma_f32_16x16x32_bf16 v[126:129], v[130:133], v[158:161], v[126:129]
	v_mfma_f32_16x16x32_bf16 v[122:125], v[138:141], v[158:161], v[122:125]
	v_mfma_f32_16x16x32_bf16 v[114:117], v[138:141], v[166:169], v[114:117]
	v_mfma_f32_16x16x32_bf16 v[118:121], v[130:133], v[166:169], v[118:121]
	v_mfma_f32_16x16x32_bf16 v[110:113], v[130:133], v[178:181], v[110:113]
	v_mfma_f32_16x16x32_bf16 v[106:109], v[138:141], v[178:181], v[106:109]
	v_mfma_f32_16x16x32_bf16 v[98:101], v[138:141], v[186:189], v[98:101]
	v_mfma_f32_16x16x32_bf16 v[102:105], v[130:133], v[186:189], v[102:105]
	v_mfma_f32_16x16x32_bf16 v[126:129], v[134:137], v[162:165], v[126:129]
	v_mfma_f32_16x16x32_bf16 v[122:125], v[142:145], v[162:165], v[122:125]
	v_mfma_f32_16x16x32_bf16 v[114:117], v[142:145], v[170:173], v[114:117]
	v_mfma_f32_16x16x32_bf16 v[118:121], v[134:137], v[170:173], v[118:121]
	v_mfma_f32_16x16x32_bf16 v[110:113], v[134:137], v[182:185], v[110:113]
	v_mfma_f32_16x16x32_bf16 v[106:109], v[142:145], v[182:185], v[106:109]
	v_mfma_f32_16x16x32_bf16 v[98:101], v[142:145], v[192:195], v[98:101]
	v_mfma_f32_16x16x32_bf16 v[102:105], v[134:137], v[192:195], v[102:105]
	s_barrier
	s_add_i32 s0, s57, s49
	v_add_u32_e32 v177, s58, v174
	s_mov_b32 m0, s0
	ds_read_b128 v[196:199], v177
	ds_read_b128 v[200:203], v177 offset:1024
	ds_read_b128 v[204:207], v177 offset:2048
	ds_read_b128 v[208:211], v177 offset:3072
	global_load_lds_dwordx4 v148, s[44:45]
	s_add_i32 m0, s0, 0x2000
	s_nop 0
	global_load_lds_dwordx4 v152, s[44:45]
	s_barrier
	s_waitcnt lgkmcnt(0)
	v_mfma_f32_16x16x32_bf16 v[94:97], v[196:199], v[158:161], v[94:97]
	v_mfma_f32_16x16x32_bf16 v[90:93], v[204:207], v[158:161], v[90:93]
	v_mfma_f32_16x16x32_bf16 v[82:85], v[204:207], v[166:169], v[82:85]
	v_mfma_f32_16x16x32_bf16 v[86:89], v[196:199], v[166:169], v[86:89]
	v_mfma_f32_16x16x32_bf16 v[78:81], v[196:199], v[178:181], v[78:81]
	v_mfma_f32_16x16x32_bf16 v[74:77], v[204:207], v[178:181], v[74:77]
	v_mfma_f32_16x16x32_bf16 v[66:69], v[204:207], v[186:189], v[66:69]
	v_mfma_f32_16x16x32_bf16 v[70:73], v[196:199], v[186:189], v[70:73]
	v_mfma_f32_16x16x32_bf16 v[94:97], v[200:203], v[162:165], v[94:97]
	v_mfma_f32_16x16x32_bf16 v[90:93], v[208:211], v[162:165], v[90:93]
	v_mfma_f32_16x16x32_bf16 v[82:85], v[208:211], v[170:173], v[82:85]
	v_mfma_f32_16x16x32_bf16 v[86:89], v[200:203], v[170:173], v[86:89]
	v_mfma_f32_16x16x32_bf16 v[78:81], v[200:203], v[182:185], v[78:81]
	v_mfma_f32_16x16x32_bf16 v[74:77], v[208:211], v[182:185], v[74:77]
	v_mfma_f32_16x16x32_bf16 v[66:69], v[208:211], v[192:195], v[66:69]
	v_mfma_f32_16x16x32_bf16 v[70:73], v[200:203], v[192:195], v[70:73]
	s_mov_b32 m0, s50
	s_barrier
	ds_read_b128 v[158:161], v176 offset:16384
	ds_read_b128 v[162:165], v176 offset:17408
	ds_read_b128 v[166:169], v176 offset:18432
	ds_read_b128 v[170:173], v176 offset:19456
	ds_read_b128 v[178:181], v176 offset:20480
	ds_read_b128 v[182:185], v176 offset:21504
	ds_read_b128 v[186:189], v176 offset:22528
	ds_read_b128 v[192:195], v176 offset:23552
	global_load_lds_dwordx4 v146, s[46:47]
	s_mov_b32 m0, s51
	s_nop 0
	global_load_lds_dwordx4 v150, s[46:47]
	s_barrier
	s_waitcnt lgkmcnt(0)
	v_mfma_f32_16x16x32_bf16 v[62:65], v[130:133], v[158:161], v[62:65]
	v_mfma_f32_16x16x32_bf16 v[58:61], v[138:141], v[158:161], v[58:61]
	v_mfma_f32_16x16x32_bf16 v[50:53], v[138:141], v[166:169], v[50:53]
	v_mfma_f32_16x16x32_bf16 v[54:57], v[130:133], v[166:169], v[54:57]
	v_mfma_f32_16x16x32_bf16 v[46:49], v[130:133], v[178:181], v[46:49]
	v_mfma_f32_16x16x32_bf16 v[42:45], v[138:141], v[178:181], v[42:45]
	v_mfma_f32_16x16x32_bf16 v[34:37], v[138:141], v[186:189], v[34:37]
	v_mfma_f32_16x16x32_bf16 v[38:41], v[130:133], v[186:189], v[38:41]
	v_mfma_f32_16x16x32_bf16 v[62:65], v[134:137], v[162:165], v[62:65]
	v_mfma_f32_16x16x32_bf16 v[58:61], v[142:145], v[162:165], v[58:61]
	v_mfma_f32_16x16x32_bf16 v[50:53], v[142:145], v[170:173], v[50:53]
	v_mfma_f32_16x16x32_bf16 v[54:57], v[134:137], v[170:173], v[54:57]
	v_mfma_f32_16x16x32_bf16 v[46:49], v[134:137], v[182:185], v[46:49]
	v_mfma_f32_16x16x32_bf16 v[42:45], v[142:145], v[182:185], v[42:45]
	v_mfma_f32_16x16x32_bf16 v[34:37], v[142:145], v[192:195], v[34:37]
	v_mfma_f32_16x16x32_bf16 v[38:41], v[134:137], v[192:195], v[38:41]
	s_barrier
	s_add_u32 s0, s44, 0x84000
	s_addc_u32 s1, s45, 0
	s_add_i32 s10, s58, s49
	s_mov_b32 m0, s10
	s_nop 0
	global_load_lds_dwordx4 v148, s[0:1]
	s_add_i32 m0, s10, 0x2000
	s_nop 0
	global_load_lds_dwordx4 v152, s[0:1]
	s_waitcnt vmcnt(6)
	s_barrier
; #define G_STAGE(bufoff, gbase, voff) do { _Pragma("unroll") for (int _i = 0; _i < 2; ++_i) \
;         __builtin_amdgcn_global_load_lds((const unsigned*)((const char*)(gbase) + (voff)[_i]), (LAS unsigned*)(lds + (bufoff) + ldsw + _i * 8192), 16, 0, 0); } while (0)
; #define G_WAIT_V(n) asm volatile("s_waitcnt vmcnt(" #n ")" ::: "memory")
; #define G_WAIT_L(n) asm volatile("s_waitcnt lgkmcnt(" #n ")" ::: "memory")
; #define G_BAR __builtin_amdgcn_s_barrier()
; #define G_SCHED __builtin_amdgcn_sched_barrier(0)
; template <int MODE  , class Epi, class Sched>
; __device__ __forceinline__ void gemm_phase(LAS unsigned char* lds, const GemmDesc g, const Sched& S, const Epi& E) {
;     ...
;             G_WAIT_V(6); G_BAR; G_MMA(1, 1, At, B1); G_BAR;
;             G_LDB(B0, 1, 0); G_SCHED; G_LDA(At, 1, 0); G_STAGE(G_SA(0, 1), a2 + hstepA, voffA);
;             G_WAIT_L(8); G_BAR; G_WAIT_L(0); G_MMA(0, 0, At, B0); G_BAR; G_SCHED;
;             G_LDB(B1, 1, 1); G_STAGE(G_SB(1, 0), b3, voffB);
;             G_BAR; G_WAIT_L(0); G_MMA(0, 1, At, B1); G_BAR;
	v_mfma_f32_16x16x32_bf16 v[30:33], v[196:199], v[158:161], v[30:33]
	v_mfma_f32_16x16x32_bf16 v[26:29], v[204:207], v[158:161], v[26:29]
	v_mfma_f32_16x16x32_bf16 v[18:21], v[204:207], v[166:169], v[18:21]
	v_mfma_f32_16x16x32_bf16 v[22:25], v[196:199], v[166:169], v[22:25]
	v_mfma_f32_16x16x32_bf16 v[14:17], v[196:199], v[178:181], v[14:17]
	v_mfma_f32_16x16x32_bf16 v[10:13], v[204:207], v[178:181], v[10:13]
	v_mfma_f32_16x16x32_bf16 v[2:5], v[204:207], v[186:189], v[2:5]
	v_mfma_f32_16x16x32_bf16 v[6:9], v[196:199], v[186:189], v[6:9]
	v_mfma_f32_16x16x32_bf16 v[30:33], v[200:203], v[162:165], v[30:33]
	v_mfma_f32_16x16x32_bf16 v[26:29], v[208:211], v[162:165], v[26:29]
	v_mfma_f32_16x16x32_bf16 v[18:21], v[208:211], v[170:173], v[18:21]
	v_mfma_f32_16x16x32_bf16 v[22:25], v[200:203], v[170:173], v[22:25]
	v_mfma_f32_16x16x32_bf16 v[14:17], v[200:203], v[182:185], v[14:17]
	v_mfma_f32_16x16x32_bf16 v[10:13], v[208:211], v[182:185], v[10:13]
	v_mfma_f32_16x16x32_bf16 v[2:5], v[208:211], v[192:195], v[2:5]
	v_mfma_f32_16x16x32_bf16 v[6:9], v[200:203], v[192:195], v[6:9]
	s_add_i32 s10, 0, 0x18000
	v_add_u32_e32 v142, s10, v174
	s_barrier
	ds_read_b128 v[130:133], v142
	ds_read_b128 v[134:137], v142 offset:1024
	ds_read_b128 v[138:141], v142 offset:2048
	ds_read_b128 v[142:145], v142 offset:3072
	s_add_u32 s0, s46, 0x84000
	s_addc_u32 s1, s47, 0
	s_mov_b32 m0, s52
	ds_read_b128 v[158:161], v176 offset:32768
	ds_read_b128 v[162:165], v176 offset:33792
	ds_read_b128 v[166:169], v176 offset:34816
	ds_read_b128 v[170:173], v176 offset:35840
	ds_read_b128 v[178:181], v176 offset:36864
	ds_read_b128 v[182:185], v176 offset:37888
	ds_read_b128 v[186:189], v176 offset:38912
	ds_read_b128 v[192:195], v176 offset:39936
	global_load_lds_dwordx4 v146, s[0:1]
	s_mov_b32 m0, s53
	s_nop 0
	global_load_lds_dwordx4 v150, s[0:1]
	s_waitcnt lgkmcnt(8)
	s_barrier
	s_waitcnt lgkmcnt(0)
	v_mfma_f32_16x16x32_bf16 v[126:129], v[130:133], v[158:161], v[126:129]
	v_mfma_f32_16x16x32_bf16 v[122:125], v[138:141], v[158:161], v[122:125]
	v_mfma_f32_16x16x32_bf16 v[114:117], v[138:141], v[166:169], v[114:117]
	v_mfma_f32_16x16x32_bf16 v[118:121], v[130:133], v[166:169], v[118:121]
	v_mfma_f32_16x16x32_bf16 v[110:113], v[130:133], v[178:181], v[110:113]
	v_mfma_f32_16x16x32_bf16 v[106:109], v[138:141], v[178:181], v[106:109]
	v_mfma_f32_16x16x32_bf16 v[98:101], v[138:141], v[186:189], v[98:101]
	v_mfma_f32_16x16x32_bf16 v[102:105], v[130:133], v[186:189], v[102:105]
	v_mfma_f32_16x16x32_bf16 v[126:129], v[134:137], v[162:165], v[126:129]
	v_mfma_f32_16x16x32_bf16 v[122:125], v[142:145], v[162:165], v[122:125]
	v_mfma_f32_16x16x32_bf16 v[114:117], v[142:145], v[170:173], v[114:117]
	v_mfma_f32_16x16x32_bf16 v[118:121], v[134:137], v[170:173], v[118:121]
	v_mfma_f32_16x16x32_bf16 v[110:113], v[134:137], v[182:185], v[110:113]
	v_mfma_f32_16x16x32_bf16 v[106:109], v[142:145], v[182:185], v[106:109]
	v_mfma_f32_16x16x32_bf16 v[98:101], v[142:145], v[192:195], v[98:101]
	v_mfma_f32_16x16x32_bf16 v[102:105], v[134:137], v[192:195], v[102:105]
	s_barrier
	s_add_i32 s11, 0, 0x1c000
	s_add_i32 s0, s10, s49
	v_add_u32_e32 v177, s11, v174
	s_add_u32 s98, s44, 0x80
	s_addc_u32 s99, s45, 0
	s_mov_b32 m0, s0
	ds_read_b128 v[196:199], v177
	ds_read_b128 v[200:203], v177 offset:1024
	ds_read_b128 v[204:207], v177 offset:2048
	ds_read_b128 v[208:211], v177 offset:3072
	global_load_lds_dwordx4 v148, s[98:99]
	s_add_i32 m0, s0, 0x2000
	s_nop 0
	global_load_lds_dwordx4 v152, s[98:99]
	s_barrier
; #define G_STAGE(bufoff, gbase, voff) do { _Pragma("unroll") for (int _i = 0; _i < 2; ++_i) \
;         __builtin_amdgcn_global_load_lds((const unsigned*)((const char*)(gbase) + (voff)[_i]), (LAS unsigned*)(lds + (bufoff) + ldsw + _i * 8192), 16, 0, 0); } while (0)
; #define G_WAIT_V(n) asm volatile("s_waitcnt vmcnt(" #n ")" ::: "memory")
; #define G_WAIT_L(n) asm volatile("s_waitcnt lgkmcnt(" #n ")" ::: "memory")
; #define G_BAR __builtin_amdgcn_s_barrier()
; #define G_SCHED __builtin_amdgcn_sched_barrier(0)
; template <int MODE  , class Epi, class Sched>
; __device__ __forceinline__ void gemm_phase(LAS unsigned char* lds, const GemmDesc g, const Sched& S, const Epi& E) {
;     ...
;             G_BAR; G_WAIT_L(0); G_MMA(0, 1, At, B1); G_BAR;
;             G_LDA(At, 1, 1); G_STAGE(G_SA(1, 0), a3, voffA);
;             G_BAR; G_WAIT_L(0); G_MMA(1, 0, At, B0); G_BAR; G_SCHED;
;             G_STAGE(G_SB(1, 1), b3 + hstepB, voffB);
;             G_WAIT_V(6); G_BAR; G_MMA(1, 1, At, B1); G_BAR;
	s_waitcnt lgkmcnt(0)
	v_mfma_f32_16x16x32_bf16 v[94:97], v[196:199], v[158:161], v[94:97]
	v_mfma_f32_16x16x32_bf16 v[90:93], v[204:207], v[158:161], v[90:93]
	v_mfma_f32_16x16x32_bf16 v[82:85], v[204:207], v[166:169], v[82:85]
	v_mfma_f32_16x16x32_bf16 v[86:89], v[196:199], v[166:169], v[86:89]
	v_mfma_f32_16x16x32_bf16 v[78:81], v[196:199], v[178:181], v[78:81]
	v_mfma_f32_16x16x32_bf16 v[74:77], v[204:207], v[178:181], v[74:77]
	v_mfma_f32_16x16x32_bf16 v[66:69], v[204:207], v[186:189], v[66:69]
	v_mfma_f32_16x16x32_bf16 v[70:73], v[196:199], v[186:189], v[70:73]
	v_mfma_f32_16x16x32_bf16 v[94:97], v[200:203], v[162:165], v[94:97]
	v_mfma_f32_16x16x32_bf16 v[90:93], v[208:211], v[162:165], v[90:93]
	v_mfma_f32_16x16x32_bf16 v[82:85], v[208:211], v[170:173], v[82:85]
	v_mfma_f32_16x16x32_bf16 v[86:89], v[200:203], v[170:173], v[86:89]
	v_mfma_f32_16x16x32_bf16 v[78:81], v[200:203], v[182:185], v[78:81]
	v_mfma_f32_16x16x32_bf16 v[74:77], v[208:211], v[182:185], v[74:77]
	v_mfma_f32_16x16x32_bf16 v[66:69], v[208:211], v[192:195], v[66:69]
	v_mfma_f32_16x16x32_bf16 v[70:73], v[200:203], v[192:195], v[70:73]
	s_mov_b32 m0, s54
	s_add_u32 s98, s46, 0x80
	s_addc_u32 s99, s47, 0
	s_barrier
	ds_read_b128 v[158:161], v176 offset:49152
	ds_read_b128 v[162:165], v176 offset:50176
	ds_read_b128 v[166:169], v176 offset:51200
	ds_read_b128 v[170:173], v176 offset:52224
	ds_read_b128 v[178:181], v176 offset:53248
	ds_read_b128 v[182:185], v176 offset:54272
	ds_read_b128 v[186:189], v176 offset:55296
	ds_read_b128 v[192:195], v176 offset:56320
	global_load_lds_dwordx4 v146, s[98:99]
	s_mov_b32 m0, s55
	s_nop 0
	global_load_lds_dwordx4 v150, s[98:99]
	s_barrier
	s_waitcnt lgkmcnt(0)
	v_mfma_f32_16x16x32_bf16 v[62:65], v[130:133], v[158:161], v[62:65]
	v_mfma_f32_16x16x32_bf16 v[58:61], v[138:141], v[158:161], v[58:61]
	v_mfma_f32_16x16x32_bf16 v[50:53], v[138:141], v[166:169], v[50:53]
	v_mfma_f32_16x16x32_bf16 v[54:57], v[130:133], v[166:169], v[54:57]
	v_mfma_f32_16x16x32_bf16 v[46:49], v[130:133], v[178:181], v[46:49]
	v_mfma_f32_16x16x32_bf16 v[42:45], v[138:141], v[178:181], v[42:45]
	v_mfma_f32_16x16x32_bf16 v[34:37], v[138:141], v[186:189], v[34:37]
	v_mfma_f32_16x16x32_bf16 v[38:41], v[130:133], v[186:189], v[38:41]
	v_mfma_f32_16x16x32_bf16 v[62:65], v[134:137], v[162:165], v[62:65]
	v_mfma_f32_16x16x32_bf16 v[58:61], v[142:145], v[162:165], v[58:61]
	v_mfma_f32_16x16x32_bf16 v[50:53], v[142:145], v[170:173], v[50:53]
	v_mfma_f32_16x16x32_bf16 v[54:57], v[134:137], v[170:173], v[54:57]
	v_mfma_f32_16x16x32_bf16 v[46:49], v[134:137], v[182:185], v[46:49]
	v_mfma_f32_16x16x32_bf16 v[42:45], v[142:145], v[182:185], v[42:45]
	v_mfma_f32_16x16x32_bf16 v[34:37], v[142:145], v[192:195], v[34:37]
	v_mfma_f32_16x16x32_bf16 v[38:41], v[134:137], v[192:195], v[38:41]
	s_barrier
	s_add_u32 s0, s44, 0x84080
	s_addc_u32 s1, s45, 0
	s_add_i32 s10, s11, s49
	s_mov_b32 m0, s10
	s_nop 0
	global_load_lds_dwordx4 v148, s[0:1]
	s_add_i32 m0, s10, 0x2000
	s_nop 0
	global_load_lds_dwordx4 v152, s[0:1]
	s_waitcnt vmcnt(6)
	s_barrier
	v_mfma_f32_16x16x32_bf16 v[30:33], v[196:199], v[158:161], v[30:33]
	s_add_i32 s71, s71, 2
	s_add_u32 s19, s19, 0x100
	s_addc_u32 s70, s70, 0
	s_cmp_gt_u32 s71, 13
	s_mov_b64 s[40:41], s[42:43]
	v_mfma_f32_16x16x32_bf16 v[26:29], v[204:207], v[158:161], v[26:29]
	v_mfma_f32_16x16x32_bf16 v[18:21], v[204:207], v[166:169], v[18:21]
	v_mfma_f32_16x16x32_bf16 v[22:25], v[196:199], v[166:169], v[22:25]
	v_mfma_f32_16x16x32_bf16 v[14:17], v[196:199], v[178:181], v[14:17]
	v_mfma_f32_16x16x32_bf16 v[10:13], v[204:207], v[178:181], v[10:13]
	v_mfma_f32_16x16x32_bf16 v[2:5], v[204:207], v[186:189], v[2:5]
	v_mfma_f32_16x16x32_bf16 v[6:9], v[196:199], v[186:189], v[6:9]
	v_mfma_f32_16x16x32_bf16 v[30:33], v[200:203], v[162:165], v[30:33]
	v_mfma_f32_16x16x32_bf16 v[26:29], v[208:211], v[162:165], v[26:29]
	v_mfma_f32_16x16x32_bf16 v[18:21], v[208:211], v[170:173], v[18:21]
	v_mfma_f32_16x16x32_bf16 v[22:25], v[200:203], v[170:173], v[22:25]
	v_mfma_f32_16x16x32_bf16 v[14:17], v[200:203], v[182:185], v[14:17]
	v_mfma_f32_16x16x32_bf16 v[10:13], v[208:211], v[182:185], v[10:13]
	v_mfma_f32_16x16x32_bf16 v[2:5], v[208:211], v[192:195], v[2:5]
	v_mfma_f32_16x16x32_bf16 v[6:9], v[200:203], v[192:195], v[6:9]
	s_cbranch_scc1 .Lkdone_sb
	s_barrier
	s_branch .LBB0_897

; #define G_STAGE(bufoff, gbase, voff) do { _Pragma("unroll") for (int _i = 0; _i < 2; ++_i) \
;         __builtin_amdgcn_global_load_lds((const unsigned*)((const char*)(gbase) + (voff)[_i]), (LAS unsigned*)(lds + (bufoff) + ldsw + _i * 8192), 16, 0, 0); } while (0)
; #define G_WAIT_V(n) asm volatile("s_waitcnt vmcnt(" #n ")" ::: "memory")
; #define G_WAIT_L(n) asm volatile("s_waitcnt lgkmcnt(" #n ")" ::: "memory")
; #define G_BAR __builtin_amdgcn_s_barrier()
; #define G_SCHED __builtin_amdgcn_sched_barrier(0)
; template <int MODE  , class Epi, class Sched>
; __device__ __forceinline__ void gemm_phase(LAS unsigned char* lds, const GemmDesc g, const Sched& S, const Epi& E) {
;     ...
;             G_LDB(B0, 0, 0); G_SCHED; G_LDA(At, 0, 0); G_STAGE(G_SA(1, 1), a1 + hstepA, voffA);
;             G_WAIT_L(8); G_BAR; G_WAIT_L(0); G_MMA(0, 0, At, B0); G_BAR; G_SCHED;
;             G_LDB(B1, 0, 1); G_STAGE(G_SB(0, 0), b2, voffB);
;             G_BAR; G_WAIT_L(0); G_MMA(0, 1, At, B1); G_BAR;
;             G_LDA(At, 0, 1); G_STAGE(G_SA(0, 0), a2, voffA);
;             G_BAR; G_WAIT_L(0); G_MMA(1, 0, At, B0); G_BAR; G_SCHED;
;             G_STAGE(G_SB(0, 1), b2 + hstepB, voffB);
;             G_WAIT_V(6); G_BAR; G_MMA(1, 1, At, B1); G_BAR;
.Lnodb_sc:
.LBB0_987:
	v_add_u32_e32 v145, s50, v142
	ds_read_b128 v[146:149], v145
	ds_read_b128 v[150:153], v145 offset:1024
	ds_read_b128 v[154:157], v145 offset:2048
	ds_read_b128 v[158:161], v145 offset:3072
	s_add_u32 s34, s20, 0x100
	s_addc_u32 s35, s21, 0
	s_cmp_eq_u32 s60, 12
	s_cselect_b32 s43, s17, s35
	s_cselect_b32 s42, s16, s34
	s_cselect_b32 s41, s3, s59
	s_cselect_b32 s40, s2, s15
	s_add_u32 s98, s20, 0x84080
	s_addc_u32 s99, s21, 0
	s_add_i32 m0, s44, 0xc000
	ds_read_b128 v[162:165], v144
	ds_read_b128 v[166:169], v144 offset:1024
	ds_read_b128 v[170:173], v144 offset:2048
	ds_read_b128 v[174:177], v144 offset:3072
	ds_read_b128 v[178:181], v144 offset:4096
	ds_read_b128 v[182:185], v144 offset:5120
	ds_read_b128 v[186:189], v144 offset:6144
	ds_read_b128 v[192:195], v144 offset:7168
	global_load_lds_dwordx4 v130, s[98:99]
	s_add_i32 m0, s44, 0xe000
	s_nop 0
	global_load_lds_dwordx4 v134, s[98:99]
	s_waitcnt lgkmcnt(8)
	s_barrier
	s_waitcnt lgkmcnt(0)
	v_mfma_f32_16x16x32_bf16 v[126:129], v[146:149], v[162:165], v[126:129]
	v_mfma_f32_16x16x32_bf16 v[122:125], v[154:157], v[162:165], v[122:125]
	v_mfma_f32_16x16x32_bf16 v[114:117], v[154:157], v[170:173], v[114:117]
	v_mfma_f32_16x16x32_bf16 v[118:121], v[146:149], v[170:173], v[118:121]
	v_mfma_f32_16x16x32_bf16 v[110:113], v[146:149], v[178:181], v[110:113]
	v_mfma_f32_16x16x32_bf16 v[106:109], v[154:157], v[178:181], v[106:109]
	v_mfma_f32_16x16x32_bf16 v[98:101], v[154:157], v[186:189], v[98:101]
	v_mfma_f32_16x16x32_bf16 v[102:105], v[146:149], v[186:189], v[102:105]
	v_mfma_f32_16x16x32_bf16 v[126:129], v[150:153], v[166:169], v[126:129]
	v_mfma_f32_16x16x32_bf16 v[122:125], v[158:161], v[166:169], v[122:125]
	v_mfma_f32_16x16x32_bf16 v[114:117], v[158:161], v[174:177], v[114:117]
	v_mfma_f32_16x16x32_bf16 v[118:121], v[150:153], v[174:177], v[118:121]
	v_mfma_f32_16x16x32_bf16 v[110:113], v[150:153], v[182:185], v[110:113]
	v_mfma_f32_16x16x32_bf16 v[106:109], v[158:161], v[182:185], v[106:109]
	v_mfma_f32_16x16x32_bf16 v[98:101], v[158:161], v[192:195], v[98:101]
	v_mfma_f32_16x16x32_bf16 v[102:105], v[150:153], v[192:195], v[102:105]
	s_barrier
	s_add_i32 s0, s50, s31
	v_add_u32_e32 v145, s51, v142
	s_mov_b32 m0, s0
	ds_read_b128 v[196:199], v145
	ds_read_b128 v[200:203], v145 offset:1024
	ds_read_b128 v[204:207], v145 offset:2048
	ds_read_b128 v[208:211], v145 offset:3072
	global_load_lds_dwordx4 v132, s[40:41]
	s_add_i32 m0, s0, 0x2000
	s_nop 0
	global_load_lds_dwordx4 v136, s[40:41]
	s_barrier
	s_waitcnt lgkmcnt(0)
	v_mfma_f32_16x16x32_bf16 v[94:97], v[196:199], v[162:165], v[94:97]
	v_mfma_f32_16x16x32_bf16 v[90:93], v[204:207], v[162:165], v[90:93]
	v_mfma_f32_16x16x32_bf16 v[82:85], v[204:207], v[170:173], v[82:85]
	v_mfma_f32_16x16x32_bf16 v[86:89], v[196:199], v[170:173], v[86:89]
	v_mfma_f32_16x16x32_bf16 v[78:81], v[196:199], v[178:181], v[78:81]
	v_mfma_f32_16x16x32_bf16 v[74:77], v[204:207], v[178:181], v[74:77]
	v_mfma_f32_16x16x32_bf16 v[66:69], v[204:207], v[186:189], v[66:69]
	v_mfma_f32_16x16x32_bf16 v[70:73], v[196:199], v[186:189], v[70:73]
	v_mfma_f32_16x16x32_bf16 v[94:97], v[200:203], v[166:169], v[94:97]
	v_mfma_f32_16x16x32_bf16 v[90:93], v[208:211], v[166:169], v[90:93]
	v_mfma_f32_16x16x32_bf16 v[82:85], v[208:211], v[174:177], v[82:85]
	v_mfma_f32_16x16x32_bf16 v[86:89], v[200:203], v[174:177], v[86:89]
	v_mfma_f32_16x16x32_bf16 v[78:81], v[200:203], v[182:185], v[78:81]
	v_mfma_f32_16x16x32_bf16 v[74:77], v[208:211], v[182:185], v[74:77]
	v_mfma_f32_16x16x32_bf16 v[66:69], v[208:211], v[192:195], v[66:69]
	v_mfma_f32_16x16x32_bf16 v[70:73], v[200:203], v[192:195], v[70:73]
	s_mov_b32 m0, s44
	s_barrier
	ds_read_b128 v[162:165], v144 offset:16384
	ds_read_b128 v[166:169], v144 offset:17408
	ds_read_b128 v[170:173], v144 offset:18432
	ds_read_b128 v[174:177], v144 offset:19456
	ds_read_b128 v[178:181], v144 offset:20480
	ds_read_b128 v[182:185], v144 offset:21504
	ds_read_b128 v[186:189], v144 offset:22528
	ds_read_b128 v[192:195], v144 offset:23552
	global_load_lds_dwordx4 v130, s[42:43]
	s_mov_b32 m0, s45
	s_nop 0
	global_load_lds_dwordx4 v134, s[42:43]
	s_barrier
	s_waitcnt lgkmcnt(0)
	v_mfma_f32_16x16x32_bf16 v[62:65], v[146:149], v[162:165], v[62:65]
	v_mfma_f32_16x16x32_bf16 v[58:61], v[154:157], v[162:165], v[58:61]
	v_mfma_f32_16x16x32_bf16 v[50:53], v[154:157], v[170:173], v[50:53]
	v_mfma_f32_16x16x32_bf16 v[54:57], v[146:149], v[170:173], v[54:57]
	v_mfma_f32_16x16x32_bf16 v[46:49], v[146:149], v[178:181], v[46:49]
	v_mfma_f32_16x16x32_bf16 v[42:45], v[154:157], v[178:181], v[42:45]
	v_mfma_f32_16x16x32_bf16 v[34:37], v[154:157], v[186:189], v[34:37]
	v_mfma_f32_16x16x32_bf16 v[38:41], v[146:149], v[186:189], v[38:41]
	v_mfma_f32_16x16x32_bf16 v[62:65], v[150:153], v[166:169], v[62:65]
	v_mfma_f32_16x16x32_bf16 v[58:61], v[158:161], v[166:169], v[58:61]
	v_mfma_f32_16x16x32_bf16 v[50:53], v[158:161], v[174:177], v[50:53]
	v_mfma_f32_16x16x32_bf16 v[54:57], v[150:153], v[174:177], v[54:57]
	v_mfma_f32_16x16x32_bf16 v[46:49], v[150:153], v[182:185], v[46:49]
	v_mfma_f32_16x16x32_bf16 v[42:45], v[158:161], v[182:185], v[42:45]
	v_mfma_f32_16x16x32_bf16 v[34:37], v[158:161], v[192:195], v[34:37]
	v_mfma_f32_16x16x32_bf16 v[38:41], v[150:153], v[192:195], v[38:41]
	s_barrier
	s_add_u32 s0, s40, 0x84000
	s_addc_u32 s1, s41, 0
	s_add_i32 s10, s51, s31
	s_mov_b32 m0, s10
	s_nop 0
	global_load_lds_dwordx4 v132, s[0:1]
	s_add_i32 m0, s10, 0x2000
	s_nop 0
	global_load_lds_dwordx4 v136, s[0:1]
	s_waitcnt vmcnt(6)
	s_barrier
; #define G_STAGE(bufoff, gbase, voff) do { _Pragma("unroll") for (int _i = 0; _i < 2; ++_i) \
;         __builtin_amdgcn_global_load_lds((const unsigned*)((const char*)(gbase) + (voff)[_i]), (LAS unsigned*)(lds + (bufoff) + ldsw + _i * 8192), 16, 0, 0); } while (0)
; #define G_WAIT_V(n) asm volatile("s_waitcnt vmcnt(" #n ")" ::: "memory")
; #define G_WAIT_L(n) asm volatile("s_waitcnt lgkmcnt(" #n ")" ::: "memory")
; #define G_BAR __builtin_amdgcn_s_barrier()
; #define G_SCHED __builtin_amdgcn_sched_barrier(0)
; template <int MODE  , class Epi, class Sched>
; __device__ __forceinline__ void gemm_phase(LAS unsigned char* lds, const GemmDesc g, const Sched& S, const Epi& E) {
;     ...
;             G_WAIT_V(6); G_BAR; G_MMA(1, 1, At, B1); G_BAR;
;             G_LDB(B0, 1, 0); G_SCHED; G_LDA(At, 1, 0); G_STAGE(G_SA(0, 1), a2 + hstepA, voffA);
;             G_WAIT_L(8); G_BAR; G_WAIT_L(0); G_MMA(0, 0, At, B0); G_BAR; G_SCHED;
;             G_LDB(B1, 1, 1); G_STAGE(G_SB(1, 0), b3, voffB);
;             G_BAR; G_WAIT_L(0); G_MMA(0, 1, At, B1); G_BAR;
	v_mfma_f32_16x16x32_bf16 v[30:33], v[196:199], v[162:165], v[30:33]
	v_mfma_f32_16x16x32_bf16 v[26:29], v[204:207], v[162:165], v[26:29]
	v_mfma_f32_16x16x32_bf16 v[18:21], v[204:207], v[170:173], v[18:21]
	v_mfma_f32_16x16x32_bf16 v[22:25], v[196:199], v[170:173], v[22:25]
	v_mfma_f32_16x16x32_bf16 v[14:17], v[196:199], v[178:181], v[14:17]
	v_mfma_f32_16x16x32_bf16 v[10:13], v[204:207], v[178:181], v[10:13]
	v_mfma_f32_16x16x32_bf16 v[2:5], v[204:207], v[186:189], v[2:5]
	v_mfma_f32_16x16x32_bf16 v[6:9], v[196:199], v[186:189], v[6:9]
	v_mfma_f32_16x16x32_bf16 v[30:33], v[200:203], v[166:169], v[30:33]
	v_mfma_f32_16x16x32_bf16 v[26:29], v[208:211], v[166:169], v[26:29]
	v_mfma_f32_16x16x32_bf16 v[18:21], v[208:211], v[174:177], v[18:21]
	v_mfma_f32_16x16x32_bf16 v[22:25], v[200:203], v[174:177], v[22:25]
	v_mfma_f32_16x16x32_bf16 v[14:17], v[200:203], v[182:185], v[14:17]
	v_mfma_f32_16x16x32_bf16 v[10:13], v[208:211], v[182:185], v[10:13]
	v_mfma_f32_16x16x32_bf16 v[2:5], v[208:211], v[192:195], v[2:5]
	v_mfma_f32_16x16x32_bf16 v[6:9], v[200:203], v[192:195], v[6:9]
	s_add_i32 s10, 0, 0x18000
	v_add_u32_e32 v145, s10, v142
	s_barrier
	ds_read_b128 v[146:149], v145
	ds_read_b128 v[150:153], v145 offset:1024
	ds_read_b128 v[154:157], v145 offset:2048
	ds_read_b128 v[158:161], v145 offset:3072
	s_add_u32 s0, s42, 0x84000
	s_addc_u32 s1, s43, 0
	s_mov_b32 m0, s46
	ds_read_b128 v[162:165], v144 offset:32768
	ds_read_b128 v[166:169], v144 offset:33792
	ds_read_b128 v[170:173], v144 offset:34816
	ds_read_b128 v[174:177], v144 offset:35840
	ds_read_b128 v[178:181], v144 offset:36864
	ds_read_b128 v[182:185], v144 offset:37888
	ds_read_b128 v[186:189], v144 offset:38912
	ds_read_b128 v[192:195], v144 offset:39936
	global_load_lds_dwordx4 v130, s[0:1]
	s_mov_b32 m0, s47
	s_nop 0
	global_load_lds_dwordx4 v134, s[0:1]
	s_waitcnt lgkmcnt(8)
	s_barrier
	s_waitcnt lgkmcnt(0)
	v_mfma_f32_16x16x32_bf16 v[126:129], v[146:149], v[162:165], v[126:129]
	v_mfma_f32_16x16x32_bf16 v[122:125], v[154:157], v[162:165], v[122:125]
	v_mfma_f32_16x16x32_bf16 v[114:117], v[154:157], v[170:173], v[114:117]
	v_mfma_f32_16x16x32_bf16 v[118:121], v[146:149], v[170:173], v[118:121]
	v_mfma_f32_16x16x32_bf16 v[110:113], v[146:149], v[178:181], v[110:113]
	v_mfma_f32_16x16x32_bf16 v[106:109], v[154:157], v[178:181], v[106:109]
	v_mfma_f32_16x16x32_bf16 v[98:101], v[154:157], v[186:189], v[98:101]
	v_mfma_f32_16x16x32_bf16 v[102:105], v[146:149], v[186:189], v[102:105]
	v_mfma_f32_16x16x32_bf16 v[126:129], v[150:153], v[166:169], v[126:129]
	v_mfma_f32_16x16x32_bf16 v[122:125], v[158:161], v[166:169], v[122:125]
	v_mfma_f32_16x16x32_bf16 v[114:117], v[158:161], v[174:177], v[114:117]
	v_mfma_f32_16x16x32_bf16 v[118:121], v[150:153], v[174:177], v[118:121]
	v_mfma_f32_16x16x32_bf16 v[110:113], v[150:153], v[182:185], v[110:113]
	v_mfma_f32_16x16x32_bf16 v[106:109], v[158:161], v[182:185], v[106:109]
	v_mfma_f32_16x16x32_bf16 v[98:101], v[158:161], v[192:195], v[98:101]
	v_mfma_f32_16x16x32_bf16 v[102:105], v[150:153], v[192:195], v[102:105]
	s_barrier
	s_add_i32 s11, 0, 0x1c000
	s_add_i32 s0, s10, s31
	v_add_u32_e32 v145, s11, v142
	s_add_u32 s98, s40, 0x80
	s_addc_u32 s99, s41, 0
	s_mov_b32 m0, s0
	ds_read_b128 v[196:199], v145
	ds_read_b128 v[200:203], v145 offset:1024
	ds_read_b128 v[204:207], v145 offset:2048
	ds_read_b128 v[208:211], v145 offset:3072
	global_load_lds_dwordx4 v132, s[98:99]
	s_add_i32 m0, s0, 0x2000
	s_nop 0
	global_load_lds_dwordx4 v136, s[98:99]
	s_barrier
; #define G_STAGE(bufoff, gbase, voff) do { _Pragma("unroll") for (int _i = 0; _i < 2; ++_i) \
;         __builtin_amdgcn_global_load_lds((const unsigned*)((const char*)(gbase) + (voff)[_i]), (LAS unsigned*)(lds + (bufoff) + ldsw + _i * 8192), 16, 0, 0); } while (0)
; #define G_WAIT_V(n) asm volatile("s_waitcnt vmcnt(" #n ")" ::: "memory")
; #define G_WAIT_L(n) asm volatile("s_waitcnt lgkmcnt(" #n ")" ::: "memory")
; #define G_BAR __builtin_amdgcn_s_barrier()
; #define G_SCHED __builtin_amdgcn_sched_barrier(0)
; template <int MODE  , class Epi, class Sched>
; __device__ __forceinline__ void gemm_phase(LAS unsigned char* lds, const GemmDesc g, const Sched& S, const Epi& E) {
;     ...
;             G_BAR; G_WAIT_L(0); G_MMA(0, 1, At, B1); G_BAR;
;             G_LDA(At, 1, 1); G_STAGE(G_SA(1, 0), a3, voffA);
;             G_BAR; G_WAIT_L(0); G_MMA(1, 0, At, B0); G_BAR; G_SCHED;
;             G_STAGE(G_SB(1, 1), b3 + hstepB, voffB);
;             G_WAIT_V(6); G_BAR; G_MMA(1, 1, At, B1); G_BAR;
	s_waitcnt lgkmcnt(0)
	v_mfma_f32_16x16x32_bf16 v[94:97], v[196:199], v[162:165], v[94:97]
	v_mfma_f32_16x16x32_bf16 v[90:93], v[204:207], v[162:165], v[90:93]
	v_mfma_f32_16x16x32_bf16 v[82:85], v[204:207], v[170:173], v[82:85]
	v_mfma_f32_16x16x32_bf16 v[86:89], v[196:199], v[170:173], v[86:89]
	v_mfma_f32_16x16x32_bf16 v[78:81], v[196:199], v[178:181], v[78:81]
	v_mfma_f32_16x16x32_bf16 v[74:77], v[204:207], v[178:181], v[74:77]
	v_mfma_f32_16x16x32_bf16 v[66:69], v[204:207], v[186:189], v[66:69]
	v_mfma_f32_16x16x32_bf16 v[70:73], v[196:199], v[186:189], v[70:73]
	v_mfma_f32_16x16x32_bf16 v[94:97], v[200:203], v[166:169], v[94:97]
	v_mfma_f32_16x16x32_bf16 v[90:93], v[208:211], v[166:169], v[90:93]
	v_mfma_f32_16x16x32_bf16 v[82:85], v[208:211], v[174:177], v[82:85]
	v_mfma_f32_16x16x32_bf16 v[86:89], v[200:203], v[174:177], v[86:89]
	v_mfma_f32_16x16x32_bf16 v[78:81], v[200:203], v[182:185], v[78:81]
	v_mfma_f32_16x16x32_bf16 v[74:77], v[208:211], v[182:185], v[74:77]
	v_mfma_f32_16x16x32_bf16 v[66:69], v[208:211], v[192:195], v[66:69]
	v_mfma_f32_16x16x32_bf16 v[70:73], v[200:203], v[192:195], v[70:73]
	s_mov_b32 m0, s48
	s_add_u32 s98, s42, 0x80
	s_addc_u32 s99, s43, 0
	s_barrier
	ds_read_b128 v[162:165], v144 offset:49152
	ds_read_b128 v[166:169], v144 offset:50176
	ds_read_b128 v[170:173], v144 offset:51200
	ds_read_b128 v[174:177], v144 offset:52224
	ds_read_b128 v[178:181], v144 offset:53248
	ds_read_b128 v[182:185], v144 offset:54272
	ds_read_b128 v[186:189], v144 offset:55296
	ds_read_b128 v[192:195], v144 offset:56320
	global_load_lds_dwordx4 v130, s[98:99]
	s_mov_b32 m0, s49
	s_nop 0
	global_load_lds_dwordx4 v134, s[98:99]
	s_barrier
	s_waitcnt lgkmcnt(0)
	v_mfma_f32_16x16x32_bf16 v[62:65], v[146:149], v[162:165], v[62:65]
	v_mfma_f32_16x16x32_bf16 v[58:61], v[154:157], v[162:165], v[58:61]
	v_mfma_f32_16x16x32_bf16 v[50:53], v[154:157], v[170:173], v[50:53]
	v_mfma_f32_16x16x32_bf16 v[54:57], v[146:149], v[170:173], v[54:57]
	v_mfma_f32_16x16x32_bf16 v[46:49], v[146:149], v[178:181], v[46:49]
	v_mfma_f32_16x16x32_bf16 v[42:45], v[154:157], v[178:181], v[42:45]
	v_mfma_f32_16x16x32_bf16 v[34:37], v[154:157], v[186:189], v[34:37]
	v_mfma_f32_16x16x32_bf16 v[38:41], v[146:149], v[186:189], v[38:41]
	v_mfma_f32_16x16x32_bf16 v[62:65], v[150:153], v[166:169], v[62:65]
	v_mfma_f32_16x16x32_bf16 v[58:61], v[158:161], v[166:169], v[58:61]
	v_mfma_f32_16x16x32_bf16 v[50:53], v[158:161], v[174:177], v[50:53]
	v_mfma_f32_16x16x32_bf16 v[54:57], v[150:153], v[174:177], v[54:57]
	v_mfma_f32_16x16x32_bf16 v[46:49], v[150:153], v[182:185], v[46:49]
	v_mfma_f32_16x16x32_bf16 v[42:45], v[158:161], v[182:185], v[42:45]
	v_mfma_f32_16x16x32_bf16 v[34:37], v[158:161], v[192:195], v[34:37]
	v_mfma_f32_16x16x32_bf16 v[38:41], v[150:153], v[192:195], v[38:41]
	s_barrier
	s_add_u32 s0, s40, 0x84080
	s_addc_u32 s1, s41, 0
	s_add_i32 s10, s11, s31
	s_mov_b32 m0, s10
	s_nop 0
	global_load_lds_dwordx4 v132, s[0:1]
	s_add_i32 m0, s10, 0x2000
	s_nop 0
	global_load_lds_dwordx4 v136, s[0:1]
	s_waitcnt vmcnt(6)
	s_barrier
	v_mfma_f32_16x16x32_bf16 v[30:33], v[196:199], v[162:165], v[30:33]
	s_add_i32 s60, s60, 2
	s_add_u32 s15, s15, 0x100
	s_addc_u32 s59, s59, 0
	s_cmp_gt_u32 s60, 13
	s_mov_b64 s[20:21], s[34:35]
	v_mfma_f32_16x16x32_bf16 v[26:29], v[204:207], v[162:165], v[26:29]
	v_mfma_f32_16x16x32_bf16 v[18:21], v[204:207], v[170:173], v[18:21]
	v_mfma_f32_16x16x32_bf16 v[22:25], v[196:199], v[170:173], v[22:25]
	v_mfma_f32_16x16x32_bf16 v[14:17], v[196:199], v[178:181], v[14:17]
	v_mfma_f32_16x16x32_bf16 v[10:13], v[204:207], v[178:181], v[10:13]
	v_mfma_f32_16x16x32_bf16 v[2:5], v[204:207], v[186:189], v[2:5]
	v_mfma_f32_16x16x32_bf16 v[6:9], v[196:199], v[186:189], v[6:9]
	v_mfma_f32_16x16x32_bf16 v[30:33], v[200:203], v[166:169], v[30:33]
	v_mfma_f32_16x16x32_bf16 v[26:29], v[208:211], v[166:169], v[26:29]
	v_mfma_f32_16x16x32_bf16 v[18:21], v[208:211], v[174:177], v[18:21]
	v_mfma_f32_16x16x32_bf16 v[22:25], v[200:203], v[174:177], v[22:25]
	v_mfma_f32_16x16x32_bf16 v[14:17], v[200:203], v[182:185], v[14:17]
	v_mfma_f32_16x16x32_bf16 v[10:13], v[208:211], v[182:185], v[10:13]
	v_mfma_f32_16x16x32_bf16 v[2:5], v[208:211], v[192:195], v[2:5]
	v_mfma_f32_16x16x32_bf16 v[6:9], v[200:203], v[192:195], v[6:9]
	s_cbranch_scc1 .Lkdone_sc
	s_barrier
	s_branch .LBB0_987

; #define G_STAGE(bufoff, gbase, voff) do { _Pragma("unroll") for (int _i = 0; _i < 2; ++_i) \
;         __builtin_amdgcn_global_load_lds((const unsigned*)((const char*)(gbase) + (voff)[_i]), (LAS unsigned*)(lds + (bufoff) + ldsw + _i * 8192), 16, 0, 0); } while (0)
; #define G_WAIT_V(n) asm volatile("s_waitcnt vmcnt(" #n ")" ::: "memory")
; #define G_WAIT_L(n) asm volatile("s_waitcnt lgkmcnt(" #n ")" ::: "memory")
; #define G_BAR __builtin_amdgcn_s_barrier()
; #define G_SCHED __builtin_amdgcn_sched_barrier(0)
; template <int MODE  , class Epi, class Sched>
; __device__ __forceinline__ void gemm_phase(LAS unsigned char* lds, const GemmDesc g, const Sched& S, const Epi& E) {
;     ...
;             G_LDB(B0, 0, 0); G_SCHED; G_LDA(At, 0, 0); G_STAGE(G_SA(1, 1), a1 + hstepA, voffA);
;             G_WAIT_L(8); G_BAR; G_WAIT_L(0); G_MMA(0, 0, At, B0); G_BAR; G_SCHED;
;             G_LDB(B1, 0, 1); G_STAGE(G_SB(0, 0), b2, voffB);
;             G_BAR; G_WAIT_L(0); G_MMA(0, 1, At, B1); G_BAR;
;             G_LDA(At, 0, 1); G_STAGE(G_SA(0, 0), a2, voffA);
;             G_BAR; G_WAIT_L(0); G_MMA(1, 0, At, B0); G_BAR; G_SCHED;
;             G_STAGE(G_SB(0, 1), b2 + hstepB, voffB);
;             G_WAIT_V(6); G_BAR; G_MMA(1, 1, At, B1); G_BAR;
.Lnodb_s1a:
.LBB0_1017:
	ds_read_b128 v[130:133], v163
	ds_read_b128 v[134:137], v163 offset:1024
	ds_read_b128 v[154:157], v163 offset:2048
	ds_read_b128 v[170:173], v163 offset:3072
	s_add_u32 s4, s2, 0x100
	s_addc_u32 s5, s3, 0
	s_cmp_eq_u32 s87, 28
	s_cselect_b32 s53, s47, s5
	s_cselect_b32 s52, s46, s4
	s_cselect_b32 s51, s49, s86
	s_cselect_b32 s50, s48, s85
	s_add_u32 s98, s2, 0x84080
	s_addc_u32 s99, s3, 0
	s_add_i32 m0, s58, 0xc000
	ds_read_b128 v[174:177], v164
	ds_read_b128 v[178:181], v164 offset:1024
	ds_read_b128 v[182:185], v164 offset:2048
	ds_read_b128 v[186:189], v164 offset:3072
	ds_read_b128 v[192:195], v164 offset:4096
	ds_read_b128 v[196:199], v164 offset:5120
	ds_read_b128 v[200:203], v164 offset:6144
	ds_read_b128 v[204:207], v164 offset:7168
	global_load_lds_dwordx4 v138, s[98:99]
	s_add_i32 m0, s58, 0xe000
	s_nop 0
	global_load_lds_dwordx4 v142, s[98:99]
	s_waitcnt lgkmcnt(8)
	s_barrier
	s_waitcnt lgkmcnt(0)
	v_mfma_f32_16x16x32_bf16 v[126:129], v[130:133], v[174:177], v[126:129]
	v_mfma_f32_16x16x32_bf16 v[122:125], v[154:157], v[174:177], v[122:125]
	v_mfma_f32_16x16x32_bf16 v[106:109], v[154:157], v[182:185], v[106:109]
	v_mfma_f32_16x16x32_bf16 v[110:113], v[130:133], v[182:185], v[110:113]
	v_mfma_f32_16x16x32_bf16 v[94:97], v[130:133], v[192:195], v[94:97]
	v_mfma_f32_16x16x32_bf16 v[90:93], v[154:157], v[192:195], v[90:93]
	v_mfma_f32_16x16x32_bf16 v[74:77], v[154:157], v[200:203], v[74:77]
	v_mfma_f32_16x16x32_bf16 v[78:81], v[130:133], v[200:203], v[78:81]
	v_mfma_f32_16x16x32_bf16 v[126:129], v[134:137], v[178:181], v[126:129]
	v_mfma_f32_16x16x32_bf16 v[122:125], v[170:173], v[178:181], v[122:125]
	v_mfma_f32_16x16x32_bf16 v[106:109], v[170:173], v[186:189], v[106:109]
	v_mfma_f32_16x16x32_bf16 v[110:113], v[134:137], v[186:189], v[110:113]
	v_mfma_f32_16x16x32_bf16 v[94:97], v[134:137], v[196:199], v[94:97]
	v_mfma_f32_16x16x32_bf16 v[90:93], v[170:173], v[196:199], v[90:93]
	v_mfma_f32_16x16x32_bf16 v[74:77], v[170:173], v[204:207], v[74:77]
	v_mfma_f32_16x16x32_bf16 v[78:81], v[134:137], v[204:207], v[78:81]
	s_barrier
	s_add_i32 s0, s66, s57
	s_mov_b32 m0, s0
	ds_read_b128 v[208:211], v165
	ds_read_b128 v[212:215], v165 offset:1024
	ds_read_b128 v[216:219], v165 offset:2048
	ds_read_b128 v[220:223], v165 offset:3072
	global_load_lds_dwordx4 v140, s[50:51]
	s_add_i32 m0, s0, 0x2000
	s_nop 0
	global_load_lds_dwordx4 v144, s[50:51]
	s_barrier
	s_waitcnt lgkmcnt(0)
	v_mfma_f32_16x16x32_bf16 v[118:121], v[208:211], v[174:177], v[118:121]
	v_mfma_f32_16x16x32_bf16 v[114:117], v[216:219], v[174:177], v[114:117]
	v_mfma_f32_16x16x32_bf16 v[98:101], v[216:219], v[182:185], v[98:101]
	v_mfma_f32_16x16x32_bf16 v[102:105], v[208:211], v[182:185], v[102:105]
	v_mfma_f32_16x16x32_bf16 v[86:89], v[208:211], v[192:195], v[86:89]
	v_mfma_f32_16x16x32_bf16 v[82:85], v[216:219], v[192:195], v[82:85]
	v_mfma_f32_16x16x32_bf16 v[66:69], v[216:219], v[200:203], v[66:69]
	v_mfma_f32_16x16x32_bf16 v[70:73], v[208:211], v[200:203], v[70:73]
	v_mfma_f32_16x16x32_bf16 v[118:121], v[212:215], v[178:181], v[118:121]
	v_mfma_f32_16x16x32_bf16 v[114:117], v[220:223], v[178:181], v[114:117]
	v_mfma_f32_16x16x32_bf16 v[98:101], v[220:223], v[186:189], v[98:101]
	v_mfma_f32_16x16x32_bf16 v[102:105], v[212:215], v[186:189], v[102:105]
	v_mfma_f32_16x16x32_bf16 v[86:89], v[212:215], v[196:199], v[86:89]
	v_mfma_f32_16x16x32_bf16 v[82:85], v[220:223], v[196:199], v[82:85]
	v_mfma_f32_16x16x32_bf16 v[66:69], v[220:223], v[204:207], v[66:69]
	v_mfma_f32_16x16x32_bf16 v[70:73], v[212:215], v[204:207], v[70:73]
	s_mov_b32 m0, s58
	s_barrier
	ds_read_b128 v[174:177], v164 offset:16384
	ds_read_b128 v[178:181], v164 offset:17408
	ds_read_b128 v[182:185], v164 offset:18432
	ds_read_b128 v[186:189], v164 offset:19456
	ds_read_b128 v[192:195], v164 offset:20480
	ds_read_b128 v[196:199], v164 offset:21504
	ds_read_b128 v[200:203], v164 offset:22528
	ds_read_b128 v[204:207], v164 offset:23552
	global_load_lds_dwordx4 v138, s[52:53]
	s_mov_b32 m0, s59
	s_nop 0
	global_load_lds_dwordx4 v142, s[52:53]
	s_barrier
	s_waitcnt lgkmcnt(0)
	v_mfma_f32_16x16x32_bf16 v[62:65], v[130:133], v[174:177], v[62:65]
	v_mfma_f32_16x16x32_bf16 v[58:61], v[154:157], v[174:177], v[58:61]
	v_mfma_f32_16x16x32_bf16 v[42:45], v[154:157], v[182:185], v[42:45]
	v_mfma_f32_16x16x32_bf16 v[46:49], v[130:133], v[182:185], v[46:49]
	v_mfma_f32_16x16x32_bf16 v[30:33], v[130:133], v[192:195], v[30:33]
	v_mfma_f32_16x16x32_bf16 v[26:29], v[154:157], v[192:195], v[26:29]
	v_mfma_f32_16x16x32_bf16 v[10:13], v[154:157], v[200:203], v[10:13]
	v_mfma_f32_16x16x32_bf16 v[14:17], v[130:133], v[200:203], v[14:17]
	v_mfma_f32_16x16x32_bf16 v[62:65], v[134:137], v[178:181], v[62:65]
	v_mfma_f32_16x16x32_bf16 v[58:61], v[170:173], v[178:181], v[58:61]
	v_mfma_f32_16x16x32_bf16 v[42:45], v[170:173], v[186:189], v[42:45]
	v_mfma_f32_16x16x32_bf16 v[46:49], v[134:137], v[186:189], v[46:49]
	v_mfma_f32_16x16x32_bf16 v[30:33], v[134:137], v[196:199], v[30:33]
	v_mfma_f32_16x16x32_bf16 v[26:29], v[170:173], v[196:199], v[26:29]
	v_mfma_f32_16x16x32_bf16 v[10:13], v[170:173], v[204:207], v[10:13]
	v_mfma_f32_16x16x32_bf16 v[14:17], v[134:137], v[204:207], v[14:17]
	s_barrier
	s_add_u32 s0, s50, 0x84000
	s_addc_u32 s1, s51, 0
	s_add_i32 s2, s67, s57
	s_mov_b32 m0, s2
	s_nop 0
	global_load_lds_dwordx4 v140, s[0:1]
	s_add_i32 m0, s2, 0x2000
	s_nop 0
	global_load_lds_dwordx4 v144, s[0:1]
	s_waitcnt vmcnt(6)
	s_barrier
; #define G_STAGE(bufoff, gbase, voff) do { _Pragma("unroll") for (int _i = 0; _i < 2; ++_i) \
;         __builtin_amdgcn_global_load_lds((const unsigned*)((const char*)(gbase) + (voff)[_i]), (LAS unsigned*)(lds + (bufoff) + ldsw + _i * 8192), 16, 0, 0); } while (0)
; #define G_WAIT_V(n) asm volatile("s_waitcnt vmcnt(" #n ")" ::: "memory")
; #define G_WAIT_L(n) asm volatile("s_waitcnt lgkmcnt(" #n ")" ::: "memory")
; #define G_BAR __builtin_amdgcn_s_barrier()
; #define G_SCHED __builtin_amdgcn_sched_barrier(0)
; template <int MODE  , class Epi, class Sched>
; __device__ __forceinline__ void gemm_phase(LAS unsigned char* lds, const GemmDesc g, const Sched& S, const Epi& E) {
;     ...
;             G_WAIT_V(6); G_BAR; G_MMA(1, 1, At, B1); G_BAR;
;             G_LDB(B0, 1, 0); G_SCHED; G_LDA(At, 1, 0); G_STAGE(G_SA(0, 1), a2 + hstepA, voffA);
;             G_WAIT_L(8); G_BAR; G_WAIT_L(0); G_MMA(0, 0, At, B0); G_BAR; G_SCHED;
;             G_LDB(B1, 1, 1); G_STAGE(G_SB(1, 0), b3, voffB);
;             G_BAR; G_WAIT_L(0); G_MMA(0, 1, At, B1); G_BAR;
	v_mfma_f32_16x16x32_bf16 v[54:57], v[208:211], v[174:177], v[54:57]
	v_mfma_f32_16x16x32_bf16 v[50:53], v[216:219], v[174:177], v[50:53]
	v_mfma_f32_16x16x32_bf16 v[34:37], v[216:219], v[182:185], v[34:37]
	v_mfma_f32_16x16x32_bf16 v[38:41], v[208:211], v[182:185], v[38:41]
	v_mfma_f32_16x16x32_bf16 v[22:25], v[208:211], v[192:195], v[22:25]
	v_mfma_f32_16x16x32_bf16 v[18:21], v[216:219], v[192:195], v[18:21]
	v_mfma_f32_16x16x32_bf16 v[2:5], v[216:219], v[200:203], v[2:5]
	v_mfma_f32_16x16x32_bf16 v[6:9], v[208:211], v[200:203], v[6:9]
	v_mfma_f32_16x16x32_bf16 v[54:57], v[212:215], v[178:181], v[54:57]
	v_mfma_f32_16x16x32_bf16 v[50:53], v[220:223], v[178:181], v[50:53]
	v_mfma_f32_16x16x32_bf16 v[34:37], v[220:223], v[186:189], v[34:37]
	v_mfma_f32_16x16x32_bf16 v[38:41], v[212:215], v[186:189], v[38:41]
	v_mfma_f32_16x16x32_bf16 v[22:25], v[212:215], v[196:199], v[22:25]
	v_mfma_f32_16x16x32_bf16 v[18:21], v[220:223], v[196:199], v[18:21]
	v_mfma_f32_16x16x32_bf16 v[2:5], v[220:223], v[204:207], v[2:5]
	v_mfma_f32_16x16x32_bf16 v[6:9], v[212:215], v[204:207], v[6:9]
	s_add_i32 s2, 0, 0x18000
	v_add_u32_e32 v146, s2, v160
	s_barrier
	ds_read_b128 v[130:133], v146
	ds_read_b128 v[134:137], v146 offset:1024
	ds_read_b128 v[154:157], v146 offset:2048
	ds_read_b128 v[170:173], v146 offset:3072
	s_add_u32 s0, s52, 0x84000
	s_addc_u32 s1, s53, 0
	s_mov_b32 m0, s60
	ds_read_b128 v[174:177], v164 offset:32768
	ds_read_b128 v[178:181], v164 offset:33792
	ds_read_b128 v[182:185], v164 offset:34816
	ds_read_b128 v[186:189], v164 offset:35840
	ds_read_b128 v[192:195], v164 offset:36864
	ds_read_b128 v[196:199], v164 offset:37888
	ds_read_b128 v[200:203], v164 offset:38912
	ds_read_b128 v[204:207], v164 offset:39936
	global_load_lds_dwordx4 v138, s[0:1]
	s_mov_b32 m0, s61
	s_nop 0
	global_load_lds_dwordx4 v142, s[0:1]
	s_waitcnt lgkmcnt(8)
	s_barrier
	s_waitcnt lgkmcnt(0)
	v_mfma_f32_16x16x32_bf16 v[126:129], v[130:133], v[174:177], v[126:129]
	v_mfma_f32_16x16x32_bf16 v[122:125], v[154:157], v[174:177], v[122:125]
	v_mfma_f32_16x16x32_bf16 v[106:109], v[154:157], v[182:185], v[106:109]
	v_mfma_f32_16x16x32_bf16 v[110:113], v[130:133], v[182:185], v[110:113]
	v_mfma_f32_16x16x32_bf16 v[94:97], v[130:133], v[192:195], v[94:97]
	v_mfma_f32_16x16x32_bf16 v[90:93], v[154:157], v[192:195], v[90:93]
	v_mfma_f32_16x16x32_bf16 v[74:77], v[154:157], v[200:203], v[74:77]
	v_mfma_f32_16x16x32_bf16 v[78:81], v[130:133], v[200:203], v[78:81]
	v_mfma_f32_16x16x32_bf16 v[126:129], v[134:137], v[178:181], v[126:129]
	v_mfma_f32_16x16x32_bf16 v[122:125], v[170:173], v[178:181], v[122:125]
	v_mfma_f32_16x16x32_bf16 v[106:109], v[170:173], v[186:189], v[106:109]
	v_mfma_f32_16x16x32_bf16 v[110:113], v[134:137], v[186:189], v[110:113]
	v_mfma_f32_16x16x32_bf16 v[94:97], v[134:137], v[196:199], v[94:97]
	v_mfma_f32_16x16x32_bf16 v[90:93], v[170:173], v[196:199], v[90:93]
	v_mfma_f32_16x16x32_bf16 v[74:77], v[170:173], v[204:207], v[74:77]
	v_mfma_f32_16x16x32_bf16 v[78:81], v[134:137], v[204:207], v[78:81]
	s_barrier
	s_add_i32 s3, 0, 0x1c000
	s_add_i32 s0, s2, s57
	v_add_u32_e32 v146, s3, v160
	s_add_u32 s98, s50, 0x80
	s_addc_u32 s99, s51, 0
	s_mov_b32 m0, s0
	ds_read_b128 v[208:211], v146
	ds_read_b128 v[212:215], v146 offset:1024
	ds_read_b128 v[216:219], v146 offset:2048
	ds_read_b128 v[220:223], v146 offset:3072
	global_load_lds_dwordx4 v140, s[98:99]
	s_add_i32 m0, s0, 0x2000
	s_nop 0
	global_load_lds_dwordx4 v144, s[98:99]
	s_barrier
; #define G_STAGE(bufoff, gbase, voff) do { _Pragma("unroll") for (int _i = 0; _i < 2; ++_i) \
;         __builtin_amdgcn_global_load_lds((const unsigned*)((const char*)(gbase) + (voff)[_i]), (LAS unsigned*)(lds + (bufoff) + ldsw + _i * 8192), 16, 0, 0); } while (0)
; #define G_WAIT_V(n) asm volatile("s_waitcnt vmcnt(" #n ")" ::: "memory")
; #define G_WAIT_L(n) asm volatile("s_waitcnt lgkmcnt(" #n ")" ::: "memory")
; #define G_BAR __builtin_amdgcn_s_barrier()
; #define G_SCHED __builtin_amdgcn_sched_barrier(0)
; template <int MODE  , class Epi, class Sched>
; __device__ __forceinline__ void gemm_phase(LAS unsigned char* lds, const GemmDesc g, const Sched& S, const Epi& E) {
;     ...
;             G_BAR; G_WAIT_L(0); G_MMA(0, 1, At, B1); G_BAR;
;             G_LDA(At, 1, 1); G_STAGE(G_SA(1, 0), a3, voffA);
;             G_BAR; G_WAIT_L(0); G_MMA(1, 0, At, B0); G_BAR; G_SCHED;
;             G_STAGE(G_SB(1, 1), b3 + hstepB, voffB);
;             G_WAIT_V(6); G_BAR; G_MMA(1, 1, At, B1); G_BAR;
	s_waitcnt lgkmcnt(0)
	v_mfma_f32_16x16x32_bf16 v[118:121], v[208:211], v[174:177], v[118:121]
	v_mfma_f32_16x16x32_bf16 v[114:117], v[216:219], v[174:177], v[114:117]
	v_mfma_f32_16x16x32_bf16 v[98:101], v[216:219], v[182:185], v[98:101]
	v_mfma_f32_16x16x32_bf16 v[102:105], v[208:211], v[182:185], v[102:105]
	v_mfma_f32_16x16x32_bf16 v[86:89], v[208:211], v[192:195], v[86:89]
	v_mfma_f32_16x16x32_bf16 v[82:85], v[216:219], v[192:195], v[82:85]
	v_mfma_f32_16x16x32_bf16 v[66:69], v[216:219], v[200:203], v[66:69]
	v_mfma_f32_16x16x32_bf16 v[70:73], v[208:211], v[200:203], v[70:73]
	v_mfma_f32_16x16x32_bf16 v[118:121], v[212:215], v[178:181], v[118:121]
	v_mfma_f32_16x16x32_bf16 v[114:117], v[220:223], v[178:181], v[114:117]
	v_mfma_f32_16x16x32_bf16 v[98:101], v[220:223], v[186:189], v[98:101]
	v_mfma_f32_16x16x32_bf16 v[102:105], v[212:215], v[186:189], v[102:105]
	v_mfma_f32_16x16x32_bf16 v[86:89], v[212:215], v[196:199], v[86:89]
	v_mfma_f32_16x16x32_bf16 v[82:85], v[220:223], v[196:199], v[82:85]
	v_mfma_f32_16x16x32_bf16 v[66:69], v[220:223], v[204:207], v[66:69]
	v_mfma_f32_16x16x32_bf16 v[70:73], v[212:215], v[204:207], v[70:73]
	s_mov_b32 m0, s64
	s_add_u32 s98, s52, 0x80
	s_addc_u32 s99, s53, 0
	s_barrier
	ds_read_b128 v[174:177], v164 offset:49152
	ds_read_b128 v[178:181], v164 offset:50176
	ds_read_b128 v[182:185], v164 offset:51200
	ds_read_b128 v[186:189], v164 offset:52224
	ds_read_b128 v[192:195], v164 offset:53248
	ds_read_b128 v[196:199], v164 offset:54272
	ds_read_b128 v[200:203], v164 offset:55296
	ds_read_b128 v[204:207], v164 offset:56320
	global_load_lds_dwordx4 v138, s[98:99]
	s_mov_b32 m0, s65
	s_nop 0
	global_load_lds_dwordx4 v142, s[98:99]
	s_barrier
	s_waitcnt lgkmcnt(0)
	v_mfma_f32_16x16x32_bf16 v[62:65], v[130:133], v[174:177], v[62:65]
	v_mfma_f32_16x16x32_bf16 v[58:61], v[154:157], v[174:177], v[58:61]
	v_mfma_f32_16x16x32_bf16 v[42:45], v[154:157], v[182:185], v[42:45]
	v_mfma_f32_16x16x32_bf16 v[46:49], v[130:133], v[182:185], v[46:49]
	v_mfma_f32_16x16x32_bf16 v[30:33], v[130:133], v[192:195], v[30:33]
	v_mfma_f32_16x16x32_bf16 v[26:29], v[154:157], v[192:195], v[26:29]
	v_mfma_f32_16x16x32_bf16 v[10:13], v[154:157], v[200:203], v[10:13]
	v_mfma_f32_16x16x32_bf16 v[14:17], v[130:133], v[200:203], v[14:17]
	v_mfma_f32_16x16x32_bf16 v[62:65], v[134:137], v[178:181], v[62:65]
	v_mfma_f32_16x16x32_bf16 v[58:61], v[170:173], v[178:181], v[58:61]
	v_mfma_f32_16x16x32_bf16 v[42:45], v[170:173], v[186:189], v[42:45]
	v_mfma_f32_16x16x32_bf16 v[46:49], v[134:137], v[186:189], v[46:49]
	v_mfma_f32_16x16x32_bf16 v[30:33], v[134:137], v[196:199], v[30:33]
	v_mfma_f32_16x16x32_bf16 v[26:29], v[170:173], v[196:199], v[26:29]
	v_mfma_f32_16x16x32_bf16 v[10:13], v[170:173], v[204:207], v[10:13]
	v_mfma_f32_16x16x32_bf16 v[14:17], v[134:137], v[204:207], v[14:17]
	s_barrier
	s_add_u32 s0, s50, 0x84080
	s_addc_u32 s1, s51, 0
	s_add_i32 s2, s3, s57
	s_mov_b32 m0, s2
	s_nop 0
	global_load_lds_dwordx4 v140, s[0:1]
	s_add_i32 m0, s2, 0x2000
	s_nop 0
	global_load_lds_dwordx4 v144, s[0:1]
	s_waitcnt vmcnt(6)
	s_barrier
	v_mfma_f32_16x16x32_bf16 v[54:57], v[208:211], v[174:177], v[54:57]
	s_add_i32 s87, s87, 2
	s_add_u32 s85, s85, 0x100
	s_addc_u32 s86, s86, 0
	s_cmp_gt_u32 s87, 29
	s_mov_b64 s[2:3], s[4:5]
	v_mfma_f32_16x16x32_bf16 v[50:53], v[216:219], v[174:177], v[50:53]
	v_mfma_f32_16x16x32_bf16 v[34:37], v[216:219], v[182:185], v[34:37]
	v_mfma_f32_16x16x32_bf16 v[38:41], v[208:211], v[182:185], v[38:41]
	v_mfma_f32_16x16x32_bf16 v[22:25], v[208:211], v[192:195], v[22:25]
	v_mfma_f32_16x16x32_bf16 v[18:21], v[216:219], v[192:195], v[18:21]
	v_mfma_f32_16x16x32_bf16 v[2:5], v[216:219], v[200:203], v[2:5]
	v_mfma_f32_16x16x32_bf16 v[6:9], v[208:211], v[200:203], v[6:9]
	v_mfma_f32_16x16x32_bf16 v[54:57], v[212:215], v[178:181], v[54:57]
	v_mfma_f32_16x16x32_bf16 v[50:53], v[220:223], v[178:181], v[50:53]
	v_mfma_f32_16x16x32_bf16 v[34:37], v[220:223], v[186:189], v[34:37]
	v_mfma_f32_16x16x32_bf16 v[38:41], v[212:215], v[186:189], v[38:41]
	v_mfma_f32_16x16x32_bf16 v[22:25], v[212:215], v[196:199], v[22:25]
	v_mfma_f32_16x16x32_bf16 v[18:21], v[220:223], v[196:199], v[18:21]
	v_mfma_f32_16x16x32_bf16 v[2:5], v[220:223], v[204:207], v[2:5]
	v_mfma_f32_16x16x32_bf16 v[6:9], v[212:215], v[204:207], v[6:9]
	s_cbranch_scc1 .Lkdone_s1a
	s_barrier
	s_branch .LBB0_1017
